# gemm<4,2> loops: two DMA chunks per MFMA pair (all tile DMAs issued within the first quarter of the k-tile)
# speedup vs baseline: 1.0043x; 1.0043x over previous
; DI f32x16 mfma(bf16x8 a, bf16x8 b, f32x16 c) { return __builtin_amdgcn_mfma_f32_32x32x16_bf16(a, b, c, 0, 0, 0); }
;     ...
;   __syncthreads();
;   DMA_ISSUE(0, 0)
;   asm volatile("s_waitcnt vmcnt(0)" ::: "memory");
;   __builtin_amdgcn_s_barrier();
;   for (int kt = 0; kt < nk; ++kt) {
;     const char* cur = lds + (kt & 1) * DBUF;
;     if (kt + 1 < nk) DMA_ISSUE((kt + 1) & 1, kt + 1)
; #pragma unroll(NTB == 1 ? 2 : 4)
;     for (int s = 0; s < 4; ++s) {
;       const int ro = ((2 * s + hh) ^ xr) * 16;
;       bf16x8 bfr[NTB];
; #pragma unroll
;       for (int tb = 0; tb < NTB; ++tb) bfr[tb] = *(const bf16x8*)(cur + bbase + tb * 32 * DROW + ro);
; #pragma unroll
;       for (int fb = 0; fb < NFB; ++fb) {
;         const bf16x8 afr = *(const bf16x8*)(cur + abase + fb * 32 * DROW + ro);
; #pragma unroll
;         for (int tb = 0; tb < NTB; ++tb) acc[tb * NFB + fb] = mfma(afr, bfr[tb], acc[tb * NFB + fb]);
;       }
;     }
;     asm volatile("s_waitcnt vmcnt(0) lgkmcnt(0)" ::: "memory");
;     __builtin_amdgcn_s_barrier();
;   }
.LBB0_149:
	s_add_i32 s8, s7, 0xffff0000
	s_and_b32 s8, s8, 0x10000
	v_add_u32_e32 v184, s8, v152
	v_add_u32_e32 v186, s8, v154
	v_add_u32_e32 v189, v184, v153
	v_add_u32_e32 v194, v186, v153
	ds_read_b128 v[234:237], v189 offset:32768
	ds_read_b128 v[238:241], v189 offset:36864
	ds_read_b128 v[250:253], v194
	ds_read_b128 v[180:183], v194 offset:4096
	ds_read_b128 v[190:193], v194 offset:8192
	ds_read_b128 v[164:167], v194 offset:12288
	v_add_u32_e32 v189, v184, v150
	v_add_u32_e32 v194, v186, v150
	ds_read_b128 v[242:245], v189 offset:32768
	ds_read_b128 v[246:249], v189 offset:36864
	s_waitcnt lgkmcnt(5)
	v_mfma_f32_32x32x16_bf16 v[114:129], v[250:253], v[234:237], v[114:129]
	v_mfma_f32_32x32x16_bf16 v[50:65], v[250:253], v[238:241], v[50:65]
	ds_read_b128 v[250:253], v194
	s_and_b32 s9, s7, 0x10000
	v_add_u32_e32 v155, s9, v151
	v_lshl_add_u64 v[156:157], v[138:139], 0, s[10:11]
	s_mov_b64 s[34:35], 0x1390080
	v_readfirstlane_b32 s9, v155
	v_add_u32_e32 v160, 0x2000, v155
	v_lshl_add_u64 v[158:159], v[156:157], 0, s[34:35]
	s_mov_b32 m0, s9
	s_mov_b64 s[34:35], 0x13b0080
	v_readfirstlane_b32 s9, v160
	v_add_u32_e32 v160, 0x4000, v155
	global_load_lds_dwordx4 v[158:159], off
	v_lshl_add_u64 v[158:159], v[156:157], 0, s[34:35]
	s_mov_b32 m0, s9
	s_mov_b64 s[34:35], 0x13d0080
	v_readfirstlane_b32 s9, v160
	global_load_lds_dwordx4 v[158:159], off
	s_waitcnt lgkmcnt(5)
	v_mfma_f32_32x32x16_bf16 v[98:113], v[180:183], v[234:237], v[98:113]
	v_mfma_f32_32x32x16_bf16 v[34:49], v[180:183], v[238:241], v[34:49]
	ds_read_b128 v[180:183], v194 offset:4096
	v_lshl_add_u64 v[158:159], v[156:157], 0, s[34:35]
	s_mov_b32 m0, s9
	s_mov_b64 s[34:35], 0x13f0080
	global_load_lds_dwordx4 v[158:159], off
	v_add_u32_e32 v158, 0x6000, v155
	v_lshl_add_u64 v[156:157], v[156:157], 0, s[34:35]
	v_readfirstlane_b32 s9, v158
	s_mov_b32 m0, s9
	v_add_u32_e32 v160, 0x8000, v155
	global_load_lds_dwordx4 v[156:157], off
	s_waitcnt lgkmcnt(5)
	v_mfma_f32_32x32x16_bf16 v[82:97], v[190:193], v[234:237], v[82:97]
	v_mfma_f32_32x32x16_bf16 v[18:33], v[190:193], v[238:241], v[18:33]
	ds_read_b128 v[190:193], v194 offset:8192
	v_lshl_add_u64 v[156:157], v[140:141], 0, s[10:11]
	v_readfirstlane_b32 s9, v160
	v_add_u32_e32 v160, 0xa000, v155
	s_add_i32 s8, s7, 0xffff0000
	v_lshl_add_u64 v[158:159], v[156:157], 0, s[68:69]
	s_mov_b32 m0, s9
	v_readfirstlane_b32 s9, v160
	v_add_u32_e32 v160, 0xc000, v155
	s_and_b32 s8, s8, 0x10000
	global_load_lds_dwordx4 v[158:159], off
	v_lshl_add_u64 v[158:159], v[156:157], 0, s[2:3]
	s_mov_b32 m0, s9
	v_readfirstlane_b32 s9, v160
	v_add_u32_e32 v155, 0xe000, v155
	s_add_i32 s8, s8, 0
	global_load_lds_dwordx4 v[158:159], off
	s_waitcnt lgkmcnt(5)
	v_mfma_f32_32x32x16_bf16 v[66:81], v[164:167], v[234:237], v[66:81]
	v_mfma_f32_32x32x16_bf16 v[2:17], v[164:167], v[238:241], v[2:17]
	ds_read_b128 v[164:167], v194 offset:12288
	v_lshl_add_u64 v[158:159], v[156:157], 0, s[14:15]
	s_mov_b32 m0, s9
	v_readfirstlane_b32 s9, v155
	global_load_lds_dwordx4 v[158:159], off
	v_lshl_add_u64 v[156:157], v[156:157], 0, s[40:41]
	s_mov_b32 m0, s9
	v_add_u32_e32 v155, s8, v152
	v_add_u32_e32 v168, s8, v154
	global_load_lds_dwordx4 v[156:157], off
	v_add_u32_e32 v189, v184, v149
	v_add_u32_e32 v194, v186, v149
	ds_read_b128 v[234:237], v189 offset:32768
	ds_read_b128 v[238:241], v189 offset:36864
	s_waitcnt lgkmcnt(5)
	v_mfma_f32_32x32x16_bf16 v[114:129], v[250:253], v[242:245], v[114:129]
	v_mfma_f32_32x32x16_bf16 v[50:65], v[250:253], v[246:249], v[50:65]
	ds_read_b128 v[250:253], v194
	s_add_u32 s10, s10, 0x80
	s_addc_u32 s11, s11, 0
	s_add_i32 s7, s7, 0x10000
	s_cmpk_eq_i32 s10, 0x780
	s_waitcnt lgkmcnt(5)
	v_mfma_f32_32x32x16_bf16 v[98:113], v[180:183], v[242:245], v[98:113]
	v_mfma_f32_32x32x16_bf16 v[34:49], v[180:183], v[246:249], v[34:49]
	ds_read_b128 v[180:183], v194 offset:4096
	s_waitcnt lgkmcnt(5)
	v_mfma_f32_32x32x16_bf16 v[82:97], v[190:193], v[242:245], v[82:97]
	v_mfma_f32_32x32x16_bf16 v[18:33], v[190:193], v[246:249], v[18:33]
	ds_read_b128 v[190:193], v194 offset:8192
	s_waitcnt lgkmcnt(5)
	v_mfma_f32_32x32x16_bf16 v[66:81], v[164:167], v[242:245], v[66:81]
	v_mfma_f32_32x32x16_bf16 v[2:17], v[164:167], v[246:249], v[2:17]
	ds_read_b128 v[164:167], v194 offset:12288
	v_add_u32_e32 v189, v184, v0
	v_add_u32_e32 v194, v186, v0
	ds_read_b128 v[242:245], v189 offset:32768
	ds_read_b128 v[246:249], v189 offset:36864
	s_waitcnt lgkmcnt(5)
	v_mfma_f32_32x32x16_bf16 v[114:129], v[250:253], v[234:237], v[114:129]
	v_mfma_f32_32x32x16_bf16 v[50:65], v[250:253], v[238:241], v[50:65]
	ds_read_b128 v[250:253], v194
	s_waitcnt lgkmcnt(5)
	v_mfma_f32_32x32x16_bf16 v[98:113], v[180:183], v[234:237], v[98:113]
	v_mfma_f32_32x32x16_bf16 v[34:49], v[180:183], v[238:241], v[34:49]
	ds_read_b128 v[180:183], v194 offset:4096
	s_waitcnt lgkmcnt(5)
	v_mfma_f32_32x32x16_bf16 v[82:97], v[190:193], v[234:237], v[82:97]
	v_mfma_f32_32x32x16_bf16 v[18:33], v[190:193], v[238:241], v[18:33]
	ds_read_b128 v[190:193], v194 offset:8192
	s_waitcnt lgkmcnt(5)
	v_mfma_f32_32x32x16_bf16 v[66:81], v[164:167], v[234:237], v[66:81]
	v_mfma_f32_32x32x16_bf16 v[2:17], v[164:167], v[238:241], v[2:17]
	ds_read_b128 v[164:167], v194 offset:12288
	s_waitcnt lgkmcnt(3)
	v_mfma_f32_32x32x16_bf16 v[114:129], v[250:253], v[242:245], v[114:129]
	v_mfma_f32_32x32x16_bf16 v[50:65], v[250:253], v[246:249], v[50:65]
	s_waitcnt lgkmcnt(2)
	v_mfma_f32_32x32x16_bf16 v[98:113], v[180:183], v[242:245], v[98:113]
	v_mfma_f32_32x32x16_bf16 v[34:49], v[180:183], v[246:249], v[34:49]
	s_waitcnt lgkmcnt(1)
	v_mfma_f32_32x32x16_bf16 v[82:97], v[190:193], v[242:245], v[82:97]
	v_mfma_f32_32x32x16_bf16 v[18:33], v[190:193], v[246:249], v[18:33]
	s_waitcnt vmcnt(0) lgkmcnt(0)
	s_barrier
; DI f32x16 mfma(bf16x8 a, bf16x8 b, f32x16 c) { return __builtin_amdgcn_mfma_f32_32x32x16_bf16(a, b, c, 0, 0, 0); }
;     ...
;   for (int kt = 0; kt < nk; ++kt) {
;     const char* cur = lds + (kt & 1) * DBUF;
;     if (kt + 1 < nk) DMA_ISSUE((kt + 1) & 1, kt + 1)
; #pragma unroll(NTB == 1 ? 2 : 4)
;     for (int s = 0; s < 4; ++s) {
;       const int ro = ((2 * s + hh) ^ xr) * 16;
;       bf16x8 bfr[NTB];
; #pragma unroll
;       for (int tb = 0; tb < NTB; ++tb) bfr[tb] = *(const bf16x8*)(cur + bbase + tb * 32 * DROW + ro);
; #pragma unroll
;       for (int fb = 0; fb < NFB; ++fb) {
;         const bf16x8 afr = *(const bf16x8*)(cur + abase + fb * 32 * DROW + ro);
; #pragma unroll
;         for (int tb = 0; tb < NTB; ++tb) acc[tb * NFB + fb] = mfma(afr, bfr[tb], acc[tb * NFB + fb]);
;       }
;     }
;     asm volatile("s_waitcnt vmcnt(0) lgkmcnt(0)" ::: "memory");
;     __builtin_amdgcn_s_barrier();
;   }
; __global__ void __launch_bounds__(512) mega(Params p) {
;     ...
;         gemm_main<4, 2>((const u16*)(ws + OFF_WFF1) + (size_t)ft * 256 * 1024, 1024, (const u16*)(ws + OFF_H) + (size_t)tt * 256 * 1024, 1024, 16, acc, lds);
;         __syncthreads();
	v_mfma_f32_32x32x16_bf16 v[66:81], v[164:167], v[242:245], v[66:81]
	v_mfma_f32_32x32x16_bf16 v[2:17], v[164:167], v[246:249], v[2:17]
	s_cbranch_scc0 .LBB0_149
	s_add_i32 s7, 0, 0x10000
	v_add_u32_e32 v162, s7, v152
	v_add_u32_e32 v163, s7, v154
	v_add_u32_e32 v151, v162, v153
	ds_read_b128 v[138:141], v151 offset:32768
	ds_read_b128 v[154:157], v151 offset:36864
	v_add_u32_e32 v151, v163, v153
	ds_read_b128 v[158:161], v151
	s_mov_b32 s8, 0x800000
	s_waitcnt lgkmcnt(0)
	v_mfma_f32_32x32x16_bf16 v[114:129], v[158:161], v[138:141], v[114:129]
	v_mfma_f32_32x32x16_bf16 v[50:65], v[158:161], v[154:157], v[50:65]
	ds_read_b128 v[158:161], v151 offset:4096
	s_waitcnt lgkmcnt(0)
	v_mfma_f32_32x32x16_bf16 v[98:113], v[158:161], v[138:141], v[98:113]
	v_mfma_f32_32x32x16_bf16 v[34:49], v[158:161], v[154:157], v[34:49]
	ds_read_b128 v[158:161], v151 offset:8192
	s_waitcnt lgkmcnt(0)
	v_mfma_f32_32x32x16_bf16 v[82:97], v[158:161], v[138:141], v[82:97]
	v_mfma_f32_32x32x16_bf16 v[18:33], v[158:161], v[154:157], v[18:33]
	ds_read_b128 v[158:161], v151 offset:12288
	v_add_u32_e32 v151, v162, v150
	v_add_u32_e32 v150, v163, v150
	s_waitcnt lgkmcnt(0)
	v_mfma_f32_32x32x16_bf16 v[66:81], v[158:161], v[138:141], v[66:81]
	v_mfma_f32_32x32x16_bf16 v[2:17], v[158:161], v[154:157], v[2:17]
	ds_read_b128 v[138:141], v151 offset:32768
	ds_read_b128 v[152:155], v151 offset:36864
	ds_read_b128 v[156:159], v150
	s_waitcnt lgkmcnt(0)
	v_mfma_f32_32x32x16_bf16 v[114:129], v[156:159], v[138:141], v[114:129]
	v_mfma_f32_32x32x16_bf16 v[50:65], v[156:159], v[152:155], v[50:65]
	ds_read_b128 v[156:159], v150 offset:4096
	s_waitcnt lgkmcnt(0)
	v_mfma_f32_32x32x16_bf16 v[98:113], v[156:159], v[138:141], v[98:113]
	v_mfma_f32_32x32x16_bf16 v[34:49], v[156:159], v[152:155], v[34:49]
	ds_read_b128 v[156:159], v150 offset:8192
	s_waitcnt lgkmcnt(0)
	v_mfma_f32_32x32x16_bf16 v[82:97], v[156:159], v[138:141], v[82:97]
	v_mfma_f32_32x32x16_bf16 v[18:33], v[156:159], v[152:155], v[18:33]
	ds_read_b128 v[156:159], v150 offset:12288
	v_add_u32_e32 v150, v162, v149
	v_add_u32_e32 v149, v163, v149
	s_waitcnt lgkmcnt(0)
	v_mfma_f32_32x32x16_bf16 v[66:81], v[156:159], v[138:141], v[66:81]
	v_mfma_f32_32x32x16_bf16 v[2:17], v[156:159], v[152:155], v[2:17]
	ds_read_b128 v[138:141], v150 offset:32768
	ds_read_b128 v[150:153], v150 offset:36864
	ds_read_b128 v[154:157], v149
	s_waitcnt lgkmcnt(0)
	v_mfma_f32_32x32x16_bf16 v[114:129], v[154:157], v[138:141], v[114:129]
	v_mfma_f32_32x32x16_bf16 v[50:65], v[154:157], v[150:153], v[50:65]
	ds_read_b128 v[154:157], v149 offset:4096
	s_waitcnt lgkmcnt(0)
	v_mfma_f32_32x32x16_bf16 v[98:113], v[154:157], v[138:141], v[98:113]
	v_mfma_f32_32x32x16_bf16 v[34:49], v[154:157], v[150:153], v[34:49]
	ds_read_b128 v[154:157], v149 offset:8192
	s_waitcnt lgkmcnt(0)
	v_mfma_f32_32x32x16_bf16 v[82:97], v[154:157], v[138:141], v[82:97]
	v_mfma_f32_32x32x16_bf16 v[18:33], v[154:157], v[150:153], v[18:33]
	ds_read_b128 v[154:157], v149 offset:12288
	v_add_u32_e32 v149, v162, v0
	v_add_u32_e32 v0, v163, v0
	s_waitcnt lgkmcnt(0)
	v_mfma_f32_32x32x16_bf16 v[66:81], v[154:157], v[138:141], v[66:81]
	v_mfma_f32_32x32x16_bf16 v[2:17], v[154:157], v[150:153], v[2:17]
	ds_read_b128 v[138:141], v149 offset:32768
	ds_read_b128 v[150:153], v149 offset:36864
	ds_read_b128 v[154:157], v0
	s_waitcnt lgkmcnt(0)
	v_mfma_f32_32x32x16_bf16 v[114:129], v[154:157], v[138:141], v[114:129]
	v_mfma_f32_32x32x16_bf16 v[50:65], v[154:157], v[150:153], v[50:65]
	ds_read_b128 v[154:157], v0 offset:4096
	s_nop 9
	v_max_f32_e32 v114, v114, v114
	v_max_f32_e32 v115, v115, v115
	v_max_f32_e32 v116, v116, v116
	v_max_f32_e32 v117, v117, v117
	v_max_f32_e32 v114, 0, v114
	v_max_f32_e32 v115, 0, v115
	s_waitcnt lgkmcnt(0)
	v_mfma_f32_32x32x16_bf16 v[98:113], v[154:157], v[138:141], v[98:113]
	v_max_f32_e32 v50, v50, v50
	v_max_f32_e32 v51, v51, v51
	v_max_f32_e32 v52, v52, v52
	v_max_f32_e32 v53, v53, v53
	v_max_f32_e32 v116, 0, v116
	v_max_f32_e32 v117, 0, v117
	v_max_f32_e32 v50, 0, v50
	v_mfma_f32_32x32x16_bf16 v[34:49], v[154:157], v[150:153], v[34:49]
	ds_read_b128 v[154:157], v0 offset:8192
	s_nop 2
	v_max_f32_e32 v98, v98, v98
	v_max_f32_e32 v99, v99, v99
	v_max_f32_e32 v100, v100, v100
	v_max_f32_e32 v101, v101, v101
	v_max_f32_e32 v98, 0, v98
	v_max_f32_e32 v99, 0, v99
	s_waitcnt lgkmcnt(0)
	v_mfma_f32_32x32x16_bf16 v[82:97], v[154:157], v[138:141], v[82:97]
	v_max_f32_e32 v34, v34, v34
	v_max_f32_e32 v35, v35, v35
	v_max_f32_e32 v36, v36, v36
	v_max_f32_e32 v37, v37, v37
	v_max_f32_e32 v100, 0, v100
	v_max_f32_e32 v101, 0, v101
	v_max_f32_e32 v51, 0, v51
	v_mfma_f32_32x32x16_bf16 v[18:33], v[154:157], v[150:153], v[18:33]
	ds_read_b128 v[154:157], v0 offset:12288
	s_waitcnt vmcnt(0) lgkmcnt(0)
	s_barrier
	s_waitcnt vmcnt(0) lgkmcnt(0)
	s_barrier
; DI float rstd4(const float* ssp, int t) {
;   return rsqrtf((ssp[t] + ssp[T_TOK + t] + ssp[2 * T_TOK + t] + ssp[3 * T_TOK + t]) * (1.f / 1024.f) + EPS);
; }
; __global__ void __launch_bounds__(512) mega(Params p) {
;     ...
;         float r2[2];
; #pragma unroll
;         for (int tb = 0; tb < 2; ++tb) r2[tb] = rstd4((const float*)(ws + OFF_SSX2), tt * 256 + wt * 64 + tb * 32 + l32);
; #pragma unroll
;         for (int tb = 0; tb < 2; ++tb)
; #pragma unroll
;           for (int fb = 0; fb < 4; ++fb)
; #pragma unroll
;             for (int jq = 0; jq < 4; ++jq) {
;               const f32x16& a = acc[tb * 4 + fb];
;               const float a0 = fmaxf(a[4 * jq], 0.f) * r2[tb], a1 = fmaxf(a[4 * jq + 1], 0.f) * r2[tb], a2 = fmaxf(a[4 * jq + 2], 0.f) * r2[tb], a3 = fmaxf(a[4 * jq + 3], 0.f) * r2[tb];
;               epi_put4(lds, wt * 64 + tb * 32 + l32, wf * 128 + fb * 32 + 8 * jq + 4 * hh, a0 * a0, a1 * a1, a2 * a2, a3 * a3);
;             }
	v_max_f32_e32 v82, v82, v82
	v_mfma_f32_32x32x16_bf16 v[66:81], v[154:157], v[138:141], v[66:81]
	v_lshl_or_b32 v138, s6, 8, v137
	v_ashrrev_i32_e32 v139, 31, v138
	v_lshl_add_u64 v[138:139], v[138:139], 2, s[52:53]
	s_mov_b32 s6, 0x20000
	flat_load_dword v141, v[138:139]
	v_max_f32_e32 v83, v83, v83
	v_max_f32_e32 v84, v84, v84
	v_mfma_f32_32x32x16_bf16 v[2:17], v[154:157], v[150:153], v[2:17]
	v_add_co_u32_e64 v150, s[6:7], s6, v138
	v_max_f32_e32 v85, v85, v85
	s_nop 0
	v_addc_co_u32_e64 v151, s[6:7], 0, v139, s[6:7]
	s_mov_b32 s6, 0x40000
	s_nop 0
	v_add_co_u32_e64 v154, s[6:7], s6, v138
	flat_load_dword v153, v[150:151]
	s_nop 0
	v_addc_co_u32_e64 v155, s[6:7], 0, v139, s[6:7]
	s_mov_b32 s6, 0x60000
	s_nop 0
	v_add_co_u32_e64 v158, s[6:7], s6, v138
	flat_load_dword v157, v[154:155]
	s_nop 0
	v_addc_co_u32_e64 v159, s[6:7], 0, v139, s[6:7]
	flat_load_dword v161, v[158:159]
	flat_load_dword v140, v[138:139] offset:128
	flat_load_dword v152, v[150:151] offset:128
	flat_load_dword v156, v[154:155] offset:128
	flat_load_dword v160, v[158:159] offset:128
	s_mov_b32 s6, 0x3a800000
	v_max_f32_e32 v66, v66, v66
	v_max_f32_e32 v67, v67, v67
	v_max_f32_e32 v68, v68, v68
	v_max_f32_e32 v69, v69, v69
	v_max_f32_e32 v18, v18, v18
	v_max_f32_e32 v19, v19, v19
	v_max_f32_e32 v20, v20, v20
	v_max_f32_e32 v21, v21, v21
	v_max_f32_e32 v2, v2, v2
	v_max_f32_e32 v3, v3, v3
	v_max_f32_e32 v4, v4, v4
	v_max_f32_e32 v5, v5, v5
	v_max_f32_e32 v82, 0, v82
	v_max_f32_e32 v83, 0, v83
	v_max_f32_e32 v84, 0, v84
	v_max_f32_e32 v85, 0, v85
	v_max_f32_e32 v66, 0, v66
	v_max_f32_e32 v67, 0, v67
	v_max_f32_e32 v68, 0, v68
	v_max_f32_e32 v69, 0, v69
	v_max_f32_e32 v52, 0, v52
	v_max_f32_e32 v53, 0, v53
	v_max_f32_e32 v34, 0, v34
	v_max_f32_e32 v35, 0, v35
	v_max_f32_e32 v36, 0, v36
	v_max_f32_e32 v37, 0, v37
	v_max_f32_e32 v18, 0, v18
	v_max_f32_e32 v19, 0, v19
	v_max_f32_e32 v20, 0, v20
	v_max_f32_e32 v21, 0, v21
	v_max_f32_e32 v2, 0, v2
	v_max_f32_e32 v3, 0, v3
	v_max_f32_e32 v4, 0, v4
	v_max_f32_e32 v5, 0, v5
	s_waitcnt vmcnt(0) lgkmcnt(0)
	v_pk_add_f32 v[138:139], v[140:141], v[152:153]
	s_nop 0
	v_pk_add_f32 v[138:139], v[138:139], v[156:157]
	s_nop 0
	v_pk_add_f32 v[138:139], v[138:139], v[160:161]
	s_nop 0
	v_pk_fma_f32 v[140:141], v[138:139], s[6:7], v[144:145] op_sel_hi:[1,0,0]
	s_nop 0
	v_mul_f32_e32 v0, 0x4b800000, v141
	v_cmp_gt_f32_e64 s[10:11], s8, v141
	v_cmp_gt_f32_e64 s[6:7], s8, v140
	s_nop 0
	v_cndmask_b32_e64 v0, v141, v0, s[10:11]
	v_rsq_f32_e32 v0, v0
	s_nop 0
	v_mul_f32_e32 v138, 0x45800000, v0
	v_cndmask_b32_e64 v138, v0, v138, s[10:11]
	v_mul_f32_e32 v0, 0x4b800000, v140
	v_cndmask_b32_e64 v0, v140, v0, s[6:7]
	v_rsq_f32_e32 v0, v0
	s_nop 0
	v_mul_f32_e32 v139, 0x45800000, v0
	v_cndmask_b32_e64 v0, v0, v139, s[6:7]
	v_pk_mul_f32 v[114:115], v[138:139], v[114:115] op_sel_hi:[0,1]
	v_pk_mul_f32 v[116:117], v[138:139], v[116:117] op_sel_hi:[0,1]
	v_pk_mul_f32 v[98:99], v[138:139], v[98:99] op_sel_hi:[0,1]
	v_pk_mul_f32 v[100:101], v[138:139], v[100:101] op_sel_hi:[0,1]
	v_pk_mul_f32 v[82:83], v[138:139], v[82:83] op_sel_hi:[0,1]
	v_pk_mul_f32 v[84:85], v[138:139], v[84:85] op_sel_hi:[0,1]
	v_pk_mul_f32 v[66:67], v[138:139], v[66:67] op_sel_hi:[0,1]
	v_pk_mul_f32 v[68:69], v[138:139], v[68:69] op_sel_hi:[0,1]
	v_pk_mul_f32 v[50:51], v[0:1], v[50:51] op_sel_hi:[0,1]
	v_pk_mul_f32 v[52:53], v[0:1], v[52:53] op_sel_hi:[0,1]
	v_pk_mul_f32 v[34:35], v[0:1], v[34:35] op_sel_hi:[0,1]
	v_pk_mul_f32 v[36:37], v[0:1], v[36:37] op_sel_hi:[0,1]
	v_pk_mul_f32 v[18:19], v[0:1], v[18:19] op_sel_hi:[0,1]
	v_pk_mul_f32 v[20:21], v[0:1], v[20:21] op_sel_hi:[0,1]
	v_pk_mul_f32 v[2:3], v[0:1], v[2:3] op_sel_hi:[0,1]
	v_pk_mul_f32 v[4:5], v[0:1], v[4:5] op_sel_hi:[0,1]
	v_pk_mul_f32 v[114:115], v[114:115], v[114:115]
	v_pk_mul_f32 v[116:117], v[116:117], v[116:117]
	v_pk_mul_f32 v[98:99], v[98:99], v[98:99]
	v_pk_mul_f32 v[100:101], v[100:101], v[100:101]
	v_pk_mul_f32 v[82:83], v[82:83], v[82:83]
	v_pk_mul_f32 v[84:85], v[84:85], v[84:85]
	v_pk_mul_f32 v[66:67], v[66:67], v[66:67]
	v_pk_mul_f32 v[68:69], v[68:69], v[68:69]
	v_pk_mul_f32 v[50:51], v[50:51], v[50:51]
	v_pk_mul_f32 v[52:53], v[52:53], v[52:53]
	v_pk_mul_f32 v[34:35], v[34:35], v[34:35]
	v_pk_mul_f32 v[36:37], v[36:37], v[36:37]
	v_pk_mul_f32 v[18:19], v[18:19], v[18:19]
	v_pk_mul_f32 v[20:21], v[20:21], v[20:21]
	v_pk_mul_f32 v[2:3], v[2:3], v[2:3]
	v_pk_mul_f32 v[4:5], v[4:5], v[4:5]
	v_cvt_pk_bf16_f32 v114, v114, v115
	v_cvt_pk_bf16_f32 v115, v116, v117
	v_max_f32_e32 v116, v118, v118
	v_max_f32_e32 v117, v119, v119
	v_max_f32_e32 v118, v120, v120
	v_max_f32_e32 v119, v121, v121
	v_cvt_pk_bf16_f32 v98, v98, v99
	v_cvt_pk_bf16_f32 v99, v100, v101
	v_max_f32_e32 v100, v102, v102
	v_max_f32_e32 v101, v103, v103
	v_max_f32_e32 v102, v104, v104
	v_max_f32_e32 v103, v105, v105
	v_cvt_pk_bf16_f32 v82, v82, v83
	v_cvt_pk_bf16_f32 v83, v84, v85
	v_max_f32_e32 v84, v86, v86
	v_max_f32_e32 v85, v87, v87
	v_max_f32_e32 v86, v88, v88
	v_max_f32_e32 v87, v89, v89
	v_cvt_pk_bf16_f32 v66, v66, v67
	v_cvt_pk_bf16_f32 v67, v68, v69
	v_max_f32_e32 v68, v70, v70
	v_max_f32_e32 v69, v71, v71
	v_max_f32_e32 v70, v72, v72
	v_max_f32_e32 v71, v73, v73
	v_cvt_pk_bf16_f32 v50, v50, v51
	v_cvt_pk_bf16_f32 v51, v52, v53
	v_max_f32_e32 v52, v54, v54
	v_max_f32_e32 v53, v55, v55
	v_max_f32_e32 v54, v56, v56
	v_max_f32_e32 v55, v57, v57
	v_cvt_pk_bf16_f32 v34, v34, v35
	v_cvt_pk_bf16_f32 v35, v36, v37
	v_max_f32_e32 v36, v38, v38
	v_max_f32_e32 v37, v39, v39
	v_max_f32_e32 v38, v40, v40
	v_max_f32_e32 v39, v41, v41
	v_cvt_pk_bf16_f32 v18, v18, v19
	v_cvt_pk_bf16_f32 v19, v20, v21
	v_max_f32_e32 v20, v22, v22
	v_max_f32_e32 v21, v23, v23
; DI unsigned pack2(float a, float b) { f2_t v = {a, b}; bf2_t r = __builtin_convertvector(v, bf2_t); return __builtin_bit_cast(unsigned, r); }
; DI void epi_put4(char* lds, int row, int col, float a, float b, float c, float d) {
;   uint2 o; o.x = pack2(a, b); o.y = pack2(c, d);
;   *(uint2*)(lds + row * EROW + col * 2) = o;
; }
; __global__ void __launch_bounds__(512) mega(Params p) {
;     ...
; #pragma unroll
;         for (int tb = 0; tb < 2; ++tb)
; #pragma unroll
;           for (int fb = 0; fb < 4; ++fb)
; #pragma unroll
;             for (int jq = 0; jq < 4; ++jq) {
;               const f32x16& a = acc[tb * 4 + fb];
;               const float a0 = fmaxf(a[4 * jq], 0.f) * r2[tb], a1 = fmaxf(a[4 * jq + 1], 0.f) * r2[tb], a2 = fmaxf(a[4 * jq + 2], 0.f) * r2[tb], a3 = fmaxf(a[4 * jq + 3], 0.f) * r2[tb];
;               epi_put4(lds, wt * 64 + tb * 32 + l32, wf * 128 + fb * 32 + 8 * jq + 4 * hh, a0 * a0, a1 * a1, a2 * a2, a3 * a3);
;             }
	v_max_f32_e32 v22, v24, v24
	v_max_f32_e32 v23, v25, v25
	v_cvt_pk_bf16_f32 v2, v2, v3
	v_cvt_pk_bf16_f32 v3, v4, v5
	v_max_f32_e32 v4, v6, v6
	v_max_f32_e32 v5, v7, v7
	v_max_f32_e32 v6, v8, v8
	v_max_f32_e32 v7, v9, v9
	v_max_f32_e32 v116, 0, v116
	v_max_f32_e32 v117, 0, v117
	v_max_f32_e32 v118, 0, v118
	v_max_f32_e32 v119, 0, v119
	v_max_f32_e32 v100, 0, v100
	v_max_f32_e32 v101, 0, v101
	v_max_f32_e32 v102, 0, v102
	v_max_f32_e32 v103, 0, v103
	v_max_f32_e32 v84, 0, v84
	v_max_f32_e32 v85, 0, v85
	v_max_f32_e32 v86, 0, v86
	v_max_f32_e32 v87, 0, v87
	v_max_f32_e32 v68, 0, v68
	v_max_f32_e32 v69, 0, v69
	v_max_f32_e32 v70, 0, v70
	v_max_f32_e32 v71, 0, v71
	v_max_f32_e32 v52, 0, v52
	v_max_f32_e32 v53, 0, v53
	v_max_f32_e32 v54, 0, v54
	v_max_f32_e32 v55, 0, v55
	v_max_f32_e32 v36, 0, v36
	v_max_f32_e32 v37, 0, v37
	v_max_f32_e32 v38, 0, v38
	v_max_f32_e32 v39, 0, v39
	v_max_f32_e32 v20, 0, v20
	v_max_f32_e32 v21, 0, v21
	v_max_f32_e32 v22, 0, v22
	v_max_f32_e32 v23, 0, v23
	v_max_f32_e32 v4, 0, v4
	v_max_f32_e32 v5, 0, v5
	v_max_f32_e32 v6, 0, v6
	v_max_f32_e32 v7, 0, v7
	v_pk_mul_f32 v[116:117], v[138:139], v[116:117] op_sel_hi:[0,1]
	v_pk_mul_f32 v[118:119], v[138:139], v[118:119] op_sel_hi:[0,1]
	v_pk_mul_f32 v[100:101], v[138:139], v[100:101] op_sel_hi:[0,1]
	v_pk_mul_f32 v[102:103], v[138:139], v[102:103] op_sel_hi:[0,1]
	v_pk_mul_f32 v[84:85], v[138:139], v[84:85] op_sel_hi:[0,1]
	v_pk_mul_f32 v[86:87], v[138:139], v[86:87] op_sel_hi:[0,1]
	v_pk_mul_f32 v[68:69], v[138:139], v[68:69] op_sel_hi:[0,1]
	v_pk_mul_f32 v[70:71], v[138:139], v[70:71] op_sel_hi:[0,1]
	v_pk_mul_f32 v[52:53], v[0:1], v[52:53] op_sel_hi:[0,1]
	v_pk_mul_f32 v[54:55], v[0:1], v[54:55] op_sel_hi:[0,1]
	v_pk_mul_f32 v[36:37], v[0:1], v[36:37] op_sel_hi:[0,1]
	v_pk_mul_f32 v[38:39], v[0:1], v[38:39] op_sel_hi:[0,1]
	v_pk_mul_f32 v[20:21], v[0:1], v[20:21] op_sel_hi:[0,1]
	v_pk_mul_f32 v[22:23], v[0:1], v[22:23] op_sel_hi:[0,1]
	v_pk_mul_f32 v[4:5], v[0:1], v[4:5] op_sel_hi:[0,1]
	v_pk_mul_f32 v[6:7], v[0:1], v[6:7] op_sel_hi:[0,1]
	v_pk_mul_f32 v[116:117], v[116:117], v[116:117]
	v_pk_mul_f32 v[118:119], v[118:119], v[118:119]
	v_pk_mul_f32 v[100:101], v[100:101], v[100:101]
	v_pk_mul_f32 v[102:103], v[102:103], v[102:103]
	v_pk_mul_f32 v[84:85], v[84:85], v[84:85]
	v_pk_mul_f32 v[86:87], v[86:87], v[86:87]
	v_pk_mul_f32 v[68:69], v[68:69], v[68:69]
	v_pk_mul_f32 v[70:71], v[70:71], v[70:71]
	v_pk_mul_f32 v[52:53], v[52:53], v[52:53]
	v_pk_mul_f32 v[54:55], v[54:55], v[54:55]
	v_pk_mul_f32 v[36:37], v[36:37], v[36:37]
	v_pk_mul_f32 v[38:39], v[38:39], v[38:39]
	v_pk_mul_f32 v[20:21], v[20:21], v[20:21]
	v_pk_mul_f32 v[22:23], v[22:23], v[22:23]
	v_pk_mul_f32 v[4:5], v[4:5], v[4:5]
	v_pk_mul_f32 v[6:7], v[6:7], v[6:7]
	v_cvt_pk_bf16_f32 v116, v116, v117
	v_cvt_pk_bf16_f32 v117, v118, v119
	v_cvt_pk_bf16_f32 v100, v100, v101
	v_cvt_pk_bf16_f32 v101, v102, v103
	v_cvt_pk_bf16_f32 v84, v84, v85
	v_cvt_pk_bf16_f32 v85, v86, v87
	v_cvt_pk_bf16_f32 v68, v68, v69
	v_cvt_pk_bf16_f32 v69, v70, v71
	v_cvt_pk_bf16_f32 v52, v52, v53
	v_cvt_pk_bf16_f32 v53, v54, v55
	v_add_u32_e32 v56, 0x4000, v143
	v_cvt_pk_bf16_f32 v36, v36, v37
	v_cvt_pk_bf16_f32 v37, v38, v39
	v_cvt_pk_bf16_f32 v20, v20, v21
	v_cvt_pk_bf16_f32 v21, v22, v23
	v_cvt_pk_bf16_f32 v4, v4, v5
	v_cvt_pk_bf16_f32 v5, v6, v7
	ds_write2_b64 v143, v[114:115], v[116:117] offset1:2
	v_max_f32_e32 v114, v122, v122
	v_max_f32_e32 v115, v123, v123
	v_max_f32_e32 v116, v124, v124
	v_max_f32_e32 v117, v125, v125
	ds_write2_b64 v143, v[98:99], v[100:101] offset0:8 offset1:10
	v_max_f32_e32 v98, v106, v106
	v_max_f32_e32 v99, v107, v107
	v_max_f32_e32 v100, v108, v108
	v_max_f32_e32 v101, v109, v109
	ds_write2_b64 v143, v[82:83], v[84:85] offset0:16 offset1:18
	v_max_f32_e32 v82, v90, v90
	v_max_f32_e32 v83, v91, v91
	v_max_f32_e32 v84, v92, v92
	v_max_f32_e32 v85, v93, v93
	ds_write2_b64 v143, v[66:67], v[68:69] offset0:24 offset1:26
	v_max_f32_e32 v66, v74, v74
	v_max_f32_e32 v67, v75, v75
	v_max_f32_e32 v68, v76, v76
	v_max_f32_e32 v69, v77, v77
	ds_write2_b64 v56, v[50:51], v[52:53] offset0:64 offset1:66
	v_max_f32_e32 v50, v58, v58
	v_max_f32_e32 v51, v59, v59
	v_max_f32_e32 v52, v60, v60
	v_max_f32_e32 v53, v61, v61
	ds_write2_b64 v56, v[34:35], v[36:37] offset0:72 offset1:74
	v_max_f32_e32 v34, v42, v42
	v_max_f32_e32 v35, v43, v43
	v_max_f32_e32 v36, v44, v44
	v_max_f32_e32 v37, v45, v45
	ds_write2_b64 v56, v[18:19], v[20:21] offset0:80 offset1:82
	v_max_f32_e32 v18, v26, v26
	v_max_f32_e32 v19, v27, v27
	v_max_f32_e32 v20, v28, v28
	v_max_f32_e32 v21, v29, v29
	ds_write2_b64 v56, v[2:3], v[4:5] offset0:88 offset1:90
	v_max_f32_e32 v2, v10, v10
	v_max_f32_e32 v3, v11, v11
	v_max_f32_e32 v4, v12, v12
	v_max_f32_e32 v5, v13, v13
	v_max_f32_e32 v114, 0, v114
	v_max_f32_e32 v115, 0, v115
	v_max_f32_e32 v116, 0, v116
	v_max_f32_e32 v117, 0, v117
	v_max_f32_e32 v98, 0, v98
	v_max_f32_e32 v99, 0, v99
	v_max_f32_e32 v100, 0, v100
	v_max_f32_e32 v101, 0, v101
	v_max_f32_e32 v82, 0, v82
	v_max_f32_e32 v83, 0, v83
	v_max_f32_e32 v84, 0, v84
	v_max_f32_e32 v85, 0, v85
	v_max_f32_e32 v66, 0, v66
	v_max_f32_e32 v67, 0, v67
	v_max_f32_e32 v68, 0, v68
	v_max_f32_e32 v69, 0, v69
	v_max_f32_e32 v50, 0, v50
	v_max_f32_e32 v51, 0, v51
	v_max_f32_e32 v52, 0, v52
	v_max_f32_e32 v53, 0, v53
	v_max_f32_e32 v34, 0, v34
	v_max_f32_e32 v35, 0, v35
	v_max_f32_e32 v36, 0, v36
	v_max_f32_e32 v37, 0, v37
	v_max_f32_e32 v18, 0, v18
	v_max_f32_e32 v19, 0, v19
	v_max_f32_e32 v20, 0, v20
	v_max_f32_e32 v21, 0, v21
	v_max_f32_e32 v2, 0, v2
	v_max_f32_e32 v3, 0, v3
	v_max_f32_e32 v4, 0, v4
	v_max_f32_e32 v5, 0, v5
; __global__ void __launch_bounds__(512) mega(Params p) {
;     ...
; #pragma unroll
;         for (int tb = 0; tb < 2; ++tb)
; #pragma unroll
;           for (int fb = 0; fb < 4; ++fb)
; #pragma unroll
;             for (int jq = 0; jq < 4; ++jq) {
;               const f32x16& a = acc[tb * 4 + fb];
;               const float a0 = fmaxf(a[4 * jq], 0.f) * r2[tb], a1 = fmaxf(a[4 * jq + 1], 0.f) * r2[tb], a2 = fmaxf(a[4 * jq + 2], 0.f) * r2[tb], a3 = fmaxf(a[4 * jq + 3], 0.f) * r2[tb];
;               epi_put4(lds, wt * 64 + tb * 32 + l32, wf * 128 + fb * 32 + 8 * jq + 4 * hh, a0 * a0, a1 * a1, a2 * a2, a3 * a3);
;             }
;         {
;           const int r0 = tid >> 5, ch = tid & 31;
;           u16* ub = (u16*)(ws + R_U) + ((size_t)(tt * 64 + ft * 4 + (ch >> 3)) * 256) * 64 + (ch & 7) * 8;
;           __syncthreads();
	v_pk_mul_f32 v[114:115], v[138:139], v[114:115] op_sel_hi:[0,1]
	v_pk_mul_f32 v[116:117], v[138:139], v[116:117] op_sel_hi:[0,1]
	v_pk_mul_f32 v[98:99], v[138:139], v[98:99] op_sel_hi:[0,1]
	v_pk_mul_f32 v[100:101], v[138:139], v[100:101] op_sel_hi:[0,1]
	v_pk_mul_f32 v[82:83], v[138:139], v[82:83] op_sel_hi:[0,1]
	v_pk_mul_f32 v[84:85], v[138:139], v[84:85] op_sel_hi:[0,1]
	v_pk_mul_f32 v[66:67], v[138:139], v[66:67] op_sel_hi:[0,1]
	v_pk_mul_f32 v[68:69], v[138:139], v[68:69] op_sel_hi:[0,1]
	v_pk_mul_f32 v[50:51], v[0:1], v[50:51] op_sel_hi:[0,1]
	v_pk_mul_f32 v[52:53], v[0:1], v[52:53] op_sel_hi:[0,1]
	v_pk_mul_f32 v[34:35], v[0:1], v[34:35] op_sel_hi:[0,1]
	v_pk_mul_f32 v[36:37], v[0:1], v[36:37] op_sel_hi:[0,1]
	v_pk_mul_f32 v[18:19], v[0:1], v[18:19] op_sel_hi:[0,1]
	v_pk_mul_f32 v[20:21], v[0:1], v[20:21] op_sel_hi:[0,1]
	v_pk_mul_f32 v[2:3], v[0:1], v[2:3] op_sel_hi:[0,1]
	v_pk_mul_f32 v[4:5], v[0:1], v[4:5] op_sel_hi:[0,1]
	v_pk_mul_f32 v[114:115], v[114:115], v[114:115]
	v_pk_mul_f32 v[116:117], v[116:117], v[116:117]
	v_pk_mul_f32 v[98:99], v[98:99], v[98:99]
	v_pk_mul_f32 v[100:101], v[100:101], v[100:101]
	v_pk_mul_f32 v[82:83], v[82:83], v[82:83]
	v_pk_mul_f32 v[84:85], v[84:85], v[84:85]
	v_pk_mul_f32 v[66:67], v[66:67], v[66:67]
	v_pk_mul_f32 v[68:69], v[68:69], v[68:69]
	v_pk_mul_f32 v[50:51], v[50:51], v[50:51]
	v_pk_mul_f32 v[52:53], v[52:53], v[52:53]
	v_pk_mul_f32 v[34:35], v[34:35], v[34:35]
	v_pk_mul_f32 v[36:37], v[36:37], v[36:37]
	v_pk_mul_f32 v[18:19], v[18:19], v[18:19]
	v_pk_mul_f32 v[20:21], v[20:21], v[20:21]
	v_pk_mul_f32 v[2:3], v[2:3], v[2:3]
	v_pk_mul_f32 v[4:5], v[4:5], v[4:5]
	v_cvt_pk_bf16_f32 v114, v114, v115
	v_cvt_pk_bf16_f32 v115, v116, v117
	v_max_f32_e32 v116, v126, v126
	v_max_f32_e32 v117, v127, v127
	v_max_f32_e32 v118, v128, v128
	v_max_f32_e32 v119, v129, v129
	v_cvt_pk_bf16_f32 v98, v98, v99
	v_cvt_pk_bf16_f32 v99, v100, v101
	v_max_f32_e32 v100, v110, v110
	v_max_f32_e32 v101, v111, v111
	v_max_f32_e32 v102, v112, v112
	v_max_f32_e32 v103, v113, v113
	v_cvt_pk_bf16_f32 v82, v82, v83
	v_cvt_pk_bf16_f32 v83, v84, v85
	v_max_f32_e32 v84, v94, v94
	v_max_f32_e32 v85, v95, v95
	v_max_f32_e32 v86, v96, v96
	v_max_f32_e32 v87, v97, v97
	v_cvt_pk_bf16_f32 v66, v66, v67
	v_cvt_pk_bf16_f32 v67, v68, v69
	v_max_f32_e32 v68, v78, v78
	v_max_f32_e32 v69, v79, v79
	v_max_f32_e32 v70, v80, v80
	v_max_f32_e32 v71, v81, v81
	v_cvt_pk_bf16_f32 v50, v50, v51
	v_cvt_pk_bf16_f32 v51, v52, v53
	v_max_f32_e32 v52, v62, v62
	v_max_f32_e32 v53, v63, v63
	v_max_f32_e32 v54, v64, v64
	v_max_f32_e32 v55, v65, v65
	v_cvt_pk_bf16_f32 v34, v34, v35
	v_cvt_pk_bf16_f32 v35, v36, v37
	v_max_f32_e32 v36, v46, v46
	v_max_f32_e32 v37, v47, v47
	v_max_f32_e32 v38, v48, v48
	v_max_f32_e32 v39, v49, v49
	v_cvt_pk_bf16_f32 v18, v18, v19
	v_cvt_pk_bf16_f32 v19, v20, v21
	v_max_f32_e32 v20, v30, v30
	v_max_f32_e32 v21, v31, v31
	v_max_f32_e32 v22, v32, v32
	v_max_f32_e32 v23, v33, v33
	v_cvt_pk_bf16_f32 v2, v2, v3
	v_cvt_pk_bf16_f32 v3, v4, v5
	v_max_f32_e32 v4, v14, v14
	v_max_f32_e32 v5, v15, v15
	v_max_f32_e32 v6, v16, v16
	v_max_f32_e32 v7, v17, v17
	v_max_f32_e32 v116, 0, v116
	v_max_f32_e32 v117, 0, v117
	v_max_f32_e32 v118, 0, v118
	v_max_f32_e32 v119, 0, v119
	v_max_f32_e32 v100, 0, v100
	v_max_f32_e32 v101, 0, v101
	v_max_f32_e32 v102, 0, v102
	v_max_f32_e32 v103, 0, v103
	v_max_f32_e32 v84, 0, v84
	v_max_f32_e32 v85, 0, v85
	v_max_f32_e32 v86, 0, v86
	v_max_f32_e32 v87, 0, v87
	v_max_f32_e32 v68, 0, v68
	v_max_f32_e32 v69, 0, v69
	v_max_f32_e32 v70, 0, v70
	v_max_f32_e32 v71, 0, v71
	v_max_f32_e32 v52, 0, v52
	v_max_f32_e32 v53, 0, v53
	v_max_f32_e32 v54, 0, v54
	v_max_f32_e32 v55, 0, v55
	v_max_f32_e32 v36, 0, v36
	v_max_f32_e32 v37, 0, v37
	v_max_f32_e32 v38, 0, v38
	v_max_f32_e32 v39, 0, v39
	v_max_f32_e32 v20, 0, v20
	v_max_f32_e32 v21, 0, v21
	v_max_f32_e32 v22, 0, v22
	v_max_f32_e32 v23, 0, v23
	v_max_f32_e32 v4, 0, v4
	v_max_f32_e32 v5, 0, v5
	v_max_f32_e32 v6, 0, v6
	v_max_f32_e32 v7, 0, v7
	v_pk_mul_f32 v[116:117], v[138:139], v[116:117] op_sel_hi:[0,1]
	v_pk_mul_f32 v[118:119], v[138:139], v[118:119] op_sel_hi:[0,1]
	v_pk_mul_f32 v[100:101], v[138:139], v[100:101] op_sel_hi:[0,1]
	v_pk_mul_f32 v[102:103], v[138:139], v[102:103] op_sel_hi:[0,1]
	v_pk_mul_f32 v[84:85], v[138:139], v[84:85] op_sel_hi:[0,1]
	v_pk_mul_f32 v[86:87], v[138:139], v[86:87] op_sel_hi:[0,1]
	v_pk_mul_f32 v[68:69], v[138:139], v[68:69] op_sel_hi:[0,1]
	v_pk_mul_f32 v[70:71], v[138:139], v[70:71] op_sel_hi:[0,1]
	v_pk_mul_f32 v[52:53], v[0:1], v[52:53] op_sel_hi:[0,1]
	v_pk_mul_f32 v[54:55], v[0:1], v[54:55] op_sel_hi:[0,1]
	v_pk_mul_f32 v[36:37], v[0:1], v[36:37] op_sel_hi:[0,1]
	v_pk_mul_f32 v[38:39], v[0:1], v[38:39] op_sel_hi:[0,1]
	v_pk_mul_f32 v[20:21], v[0:1], v[20:21] op_sel_hi:[0,1]
	v_pk_mul_f32 v[22:23], v[0:1], v[22:23] op_sel_hi:[0,1]
	v_pk_mul_f32 v[4:5], v[0:1], v[4:5] op_sel_hi:[0,1]
	v_pk_mul_f32 v[6:7], v[0:1], v[6:7] op_sel_hi:[0,1]
	v_pk_mul_f32 v[116:117], v[116:117], v[116:117]
	v_pk_mul_f32 v[118:119], v[118:119], v[118:119]
	v_pk_mul_f32 v[100:101], v[100:101], v[100:101]
	v_pk_mul_f32 v[102:103], v[102:103], v[102:103]
	v_pk_mul_f32 v[84:85], v[84:85], v[84:85]
	v_pk_mul_f32 v[86:87], v[86:87], v[86:87]
	v_pk_mul_f32 v[68:69], v[68:69], v[68:69]
	v_pk_mul_f32 v[70:71], v[70:71], v[70:71]
	v_pk_mul_f32 v[52:53], v[52:53], v[52:53]
	v_pk_mul_f32 v[54:55], v[54:55], v[54:55]
	v_pk_mul_f32 v[36:37], v[36:37], v[36:37]
	v_pk_mul_f32 v[38:39], v[38:39], v[38:39]
	v_pk_mul_f32 v[20:21], v[20:21], v[20:21]
	v_pk_mul_f32 v[22:23], v[22:23], v[22:23]
	v_pk_mul_f32 v[4:5], v[4:5], v[4:5]
	v_pk_mul_f32 v[6:7], v[6:7], v[6:7]
	v_cvt_pk_bf16_f32 v116, v116, v117
	v_cvt_pk_bf16_f32 v117, v118, v119
	v_cvt_pk_bf16_f32 v100, v100, v101
	v_cvt_pk_bf16_f32 v101, v102, v103
	v_cvt_pk_bf16_f32 v84, v84, v85
	v_cvt_pk_bf16_f32 v85, v86, v87
	v_cvt_pk_bf16_f32 v68, v68, v69
	v_cvt_pk_bf16_f32 v69, v70, v71
	v_cvt_pk_bf16_f32 v52, v52, v53
	v_cvt_pk_bf16_f32 v53, v54, v55
	v_cvt_pk_bf16_f32 v36, v36, v37
	v_cvt_pk_bf16_f32 v37, v38, v39
	v_cvt_pk_bf16_f32 v20, v20, v21
	v_cvt_pk_bf16_f32 v21, v22, v23
	v_cvt_pk_bf16_f32 v4, v4, v5
	v_cvt_pk_bf16_f32 v5, v6, v7
	ds_write2_b64 v143, v[114:115], v[116:117] offset0:4 offset1:6
	ds_write2_b64 v143, v[98:99], v[100:101] offset0:12 offset1:14
	ds_write2_b64 v143, v[82:83], v[84:85] offset0:20 offset1:22
	ds_write2_b64 v143, v[66:67], v[68:69] offset0:28 offset1:30
	ds_write2_b64 v56, v[50:51], v[52:53] offset0:68 offset1:70
	ds_write2_b64 v56, v[34:35], v[36:37] offset0:76 offset1:78
	ds_write2_b64 v56, v[18:19], v[20:21] offset0:84 offset1:86
	ds_write2_b64 v56, v[2:3], v[4:5] offset0:92 offset1:94
	s_waitcnt lgkmcnt(0)
	s_barrier
; __global__ void __launch_bounds__(512) mega(Params p) {
;     ...
;         {
;           const int r0 = tid >> 5, ch = tid & 31;
;           u16* ub = (u16*)(ws + R_U) + ((size_t)(tt * 64 + ft * 4 + (ch >> 3)) * 256) * 64 + (ch & 7) * 8;
;           __syncthreads();
; #pragma unroll 4
;           for (int r = r0; r < 256; r += 16) __builtin_nontemporal_store(*(const u32x4*)(lds + r * EROW + ch * 16), (u32x4*)(ub + (size_t)r * 64));
	s_and_saveexec_b64 s[10:11], vcc
	s_cbranch_execz .LBB0_147
	v_mov_b32_e32 v10, v130
	s_and_saveexec_b64 s[8:9], s[0:1]
	s_cbranch_execz .LBB0_155
	s_lshl_b32 s7, s59, 4
	s_lshl_b32 s33, s66, 2
	s_lshl_b32 s6, s64, 6
	s_add_i32 s7, s33, s7
	s_add_i32 s7, s7, s6
	v_or_b32_e32 v2, s7, v142
	v_ashrrev_i32_e32 v3, 31, v2
	v_lshlrev_b64 v[2:3], 15, v[2:3]
	v_lshl_add_u64 v[2:3], v[134:135], 0, v[2:3]
	s_mov_b64 s[34:35], 0
	v_mov_b32_e32 v0, v148
	v_mov_b32_e32 v4, v131
	v_mov_b32_e32 v10, v130
	s_mov_b64 s[68:69], 0x800

; DI f32x16 mfma(bf16x8 a, bf16x8 b, f32x16 c) { return __builtin_amdgcn_mfma_f32_32x32x16_bf16(a, b, c, 0, 0, 0); }
;     ...
;   __syncthreads();
;   DMA_ISSUE(0, 0)
;   asm volatile("s_waitcnt vmcnt(0)" ::: "memory");
;   __builtin_amdgcn_s_barrier();
;   for (int kt = 0; kt < nk; ++kt) {
;     const char* cur = lds + (kt & 1) * DBUF;
;     if (kt + 1 < nk) DMA_ISSUE((kt + 1) & 1, kt + 1)
; #pragma unroll(NTB == 1 ? 2 : 4)
;     for (int s = 0; s < 4; ++s) {
;       const int ro = ((2 * s + hh) ^ xr) * 16;
;       bf16x8 bfr[NTB];
; #pragma unroll
;       for (int tb = 0; tb < NTB; ++tb) bfr[tb] = *(const bf16x8*)(cur + bbase + tb * 32 * DROW + ro);
; #pragma unroll
;       for (int fb = 0; fb < NFB; ++fb) {
;         const bf16x8 afr = *(const bf16x8*)(cur + abase + fb * 32 * DROW + ro);
; #pragma unroll
;         for (int tb = 0; tb < NTB; ++tb) acc[tb * NFB + fb] = mfma(afr, bfr[tb], acc[tb * NFB + fb]);
;       }
;     }
;     asm volatile("s_waitcnt vmcnt(0) lgkmcnt(0)" ::: "memory");
;     __builtin_amdgcn_s_barrier();
;   }
.LBB0_170:
	s_add_i32 s8, s5, 0xffff0000
	s_and_b32 s8, s8, 0x10000
	v_add_u32_e32 v184, s8, v143
	v_add_u32_e32 v186, s8, v149
	v_add_u32_e32 v189, v184, v148
	v_add_u32_e32 v194, v186, v148
	ds_read_b128 v[234:237], v189 offset:32768
	ds_read_b128 v[238:241], v189 offset:36864
	ds_read_b128 v[250:253], v194
	ds_read_b128 v[180:183], v194 offset:4096
	ds_read_b128 v[190:193], v194 offset:8192
	ds_read_b128 v[158:161], v194 offset:12288
	v_add_u32_e32 v189, v184, v141
	v_add_u32_e32 v194, v186, v141
	ds_read_b128 v[242:245], v189 offset:32768
	ds_read_b128 v[246:249], v189 offset:36864
	s_waitcnt lgkmcnt(5)
	v_mfma_f32_32x32x16_bf16 v[114:129], v[250:253], v[234:237], v[114:129]
	v_mfma_f32_32x32x16_bf16 v[50:65], v[250:253], v[238:241], v[50:65]
	ds_read_b128 v[250:253], v194
	s_and_b32 s9, s5, 0x10000
	v_add_u32_e32 v154, s9, v142
	v_lshl_add_u64 v[150:151], v[134:135], 0, s[66:67]
	v_readfirstlane_b32 s9, v154
	v_add_u32_e32 v155, 0x2000, v154
	v_lshl_add_u64 v[152:153], v[150:151], 0, s[56:57]
	s_mov_b32 m0, s9
	v_readfirstlane_b32 s9, v155
	v_add_u32_e32 v155, 0x4000, v154
	global_load_lds_dwordx4 v[152:153], off
	v_lshl_add_u64 v[152:153], v[150:151], 0, s[68:69]
	s_mov_b32 m0, s9
	v_readfirstlane_b32 s9, v155
	global_load_lds_dwordx4 v[152:153], off
	s_waitcnt lgkmcnt(5)
	v_mfma_f32_32x32x16_bf16 v[98:113], v[180:183], v[234:237], v[98:113]
	v_mfma_f32_32x32x16_bf16 v[34:49], v[180:183], v[238:241], v[34:49]
	ds_read_b128 v[180:183], v194 offset:4096
	v_lshl_add_u64 v[152:153], v[150:151], 0, s[58:59]
	s_mov_b32 m0, s9
	v_lshl_add_u64 v[150:151], v[150:151], 0, s[70:71]
	global_load_lds_dwordx4 v[152:153], off
	v_add_u32_e32 v152, 0x6000, v154
	v_add_u32_e32 v155, 0x8000, v154
	v_readfirstlane_b32 s9, v152
	s_mov_b32 m0, s9
	v_readfirstlane_b32 s9, v155
	global_load_lds_dwordx4 v[150:151], off
	s_waitcnt lgkmcnt(5)
	v_mfma_f32_32x32x16_bf16 v[82:97], v[190:193], v[234:237], v[82:97]
	v_mfma_f32_32x32x16_bf16 v[18:33], v[190:193], v[238:241], v[18:33]
	ds_read_b128 v[190:193], v194 offset:8192
	v_lshl_add_u64 v[150:151], v[136:137], 0, s[66:67]
	v_add_u32_e32 v155, 0xa000, v154
	v_lshl_add_u64 v[152:153], v[150:151], 0, s[56:57]
	s_mov_b32 m0, s9
	v_readfirstlane_b32 s9, v155
	v_add_u32_e32 v155, 0xc000, v154
	global_load_lds_dwordx4 v[152:153], off
	v_lshl_add_u64 v[152:153], v[150:151], 0, s[68:69]
	s_mov_b32 m0, s9
	v_readfirstlane_b32 s9, v155
	s_add_i32 s8, s5, 0xffff0000
	global_load_lds_dwordx4 v[152:153], off
	s_waitcnt lgkmcnt(5)
	v_mfma_f32_32x32x16_bf16 v[66:81], v[158:161], v[234:237], v[66:81]
	v_mfma_f32_32x32x16_bf16 v[2:17], v[158:161], v[238:241], v[2:17]
	ds_read_b128 v[158:161], v194 offset:12288
	v_lshl_add_u64 v[152:153], v[150:151], 0, s[58:59]
	s_mov_b32 m0, s9
	s_and_b32 s8, s8, 0x10000
	global_load_lds_dwordx4 v[152:153], off
	v_add_u32_e32 v152, 0xe000, v154
	s_add_i32 s8, s8, 0
	v_readfirstlane_b32 s9, v152
	v_lshl_add_u64 v[150:151], v[150:151], 0, s[70:71]
	s_mov_b32 m0, s9
	v_add_u32_e32 v162, s8, v143
	v_add_u32_e32 v163, s8, v149
	global_load_lds_dwordx4 v[150:151], off
	v_add_u32_e32 v189, v184, v140
	v_add_u32_e32 v194, v186, v140
	ds_read_b128 v[234:237], v189 offset:32768
	ds_read_b128 v[238:241], v189 offset:36864
	s_waitcnt lgkmcnt(5)
	v_mfma_f32_32x32x16_bf16 v[114:129], v[250:253], v[242:245], v[114:129]
	v_mfma_f32_32x32x16_bf16 v[50:65], v[250:253], v[246:249], v[50:65]
	ds_read_b128 v[250:253], v194
	s_add_u32 s66, s66, 0x8000
	s_addc_u32 s67, s67, 0
	s_add_i32 s5, s5, 0x10000
	s_cmp_eq_u32 s66, 0x1f8000
	s_waitcnt lgkmcnt(5)
	v_mfma_f32_32x32x16_bf16 v[98:113], v[180:183], v[242:245], v[98:113]
	v_mfma_f32_32x32x16_bf16 v[34:49], v[180:183], v[246:249], v[34:49]
	ds_read_b128 v[180:183], v194 offset:4096
	s_waitcnt lgkmcnt(5)
	v_mfma_f32_32x32x16_bf16 v[82:97], v[190:193], v[242:245], v[82:97]
	v_mfma_f32_32x32x16_bf16 v[18:33], v[190:193], v[246:249], v[18:33]
	ds_read_b128 v[190:193], v194 offset:8192
	s_waitcnt lgkmcnt(5)
	v_mfma_f32_32x32x16_bf16 v[66:81], v[158:161], v[242:245], v[66:81]
	v_mfma_f32_32x32x16_bf16 v[2:17], v[158:161], v[246:249], v[2:17]
	ds_read_b128 v[158:161], v194 offset:12288
	v_add_u32_e32 v189, v184, v0
	v_add_u32_e32 v194, v186, v0
	ds_read_b128 v[242:245], v189 offset:32768
	ds_read_b128 v[246:249], v189 offset:36864
	s_waitcnt lgkmcnt(5)
	v_mfma_f32_32x32x16_bf16 v[114:129], v[250:253], v[234:237], v[114:129]
	v_mfma_f32_32x32x16_bf16 v[50:65], v[250:253], v[238:241], v[50:65]
	ds_read_b128 v[250:253], v194
	s_waitcnt lgkmcnt(5)
	v_mfma_f32_32x32x16_bf16 v[98:113], v[180:183], v[234:237], v[98:113]
	v_mfma_f32_32x32x16_bf16 v[34:49], v[180:183], v[238:241], v[34:49]
	ds_read_b128 v[180:183], v194 offset:4096
	s_waitcnt lgkmcnt(5)
	v_mfma_f32_32x32x16_bf16 v[82:97], v[190:193], v[234:237], v[82:97]
	v_mfma_f32_32x32x16_bf16 v[18:33], v[190:193], v[238:241], v[18:33]
	ds_read_b128 v[190:193], v194 offset:8192
	s_waitcnt lgkmcnt(5)
	v_mfma_f32_32x32x16_bf16 v[66:81], v[158:161], v[234:237], v[66:81]
	v_mfma_f32_32x32x16_bf16 v[2:17], v[158:161], v[238:241], v[2:17]
	ds_read_b128 v[158:161], v194 offset:12288
	s_waitcnt lgkmcnt(3)
	v_mfma_f32_32x32x16_bf16 v[114:129], v[250:253], v[242:245], v[114:129]
	v_mfma_f32_32x32x16_bf16 v[50:65], v[250:253], v[246:249], v[50:65]
	s_waitcnt lgkmcnt(2)
	v_mfma_f32_32x32x16_bf16 v[98:113], v[180:183], v[242:245], v[98:113]
	v_mfma_f32_32x32x16_bf16 v[34:49], v[180:183], v[246:249], v[34:49]
	s_waitcnt lgkmcnt(1)
	v_mfma_f32_32x32x16_bf16 v[82:97], v[190:193], v[242:245], v[82:97]
	v_mfma_f32_32x32x16_bf16 v[18:33], v[190:193], v[246:249], v[18:33]
	s_waitcnt vmcnt(0) lgkmcnt(0)
	s_barrier
; DI f32x16 mfma(bf16x8 a, bf16x8 b, f32x16 c) { return __builtin_amdgcn_mfma_f32_32x32x16_bf16(a, b, c, 0, 0, 0); }
;     ...
;   for (int kt = 0; kt < nk; ++kt) {
;     const char* cur = lds + (kt & 1) * DBUF;
;     if (kt + 1 < nk) DMA_ISSUE((kt + 1) & 1, kt + 1)
; #pragma unroll(NTB == 1 ? 2 : 4)
;     for (int s = 0; s < 4; ++s) {
;       const int ro = ((2 * s + hh) ^ xr) * 16;
;       bf16x8 bfr[NTB];
; #pragma unroll
;       for (int tb = 0; tb < NTB; ++tb) bfr[tb] = *(const bf16x8*)(cur + bbase + tb * 32 * DROW + ro);
; #pragma unroll
;       for (int fb = 0; fb < NFB; ++fb) {
;         const bf16x8 afr = *(const bf16x8*)(cur + abase + fb * 32 * DROW + ro);
; #pragma unroll
;         for (int tb = 0; tb < NTB; ++tb) acc[tb * NFB + fb] = mfma(afr, bfr[tb], acc[tb * NFB + fb]);
;       }
;     }
;     asm volatile("s_waitcnt vmcnt(0) lgkmcnt(0)" ::: "memory");
;     __builtin_amdgcn_s_barrier();
;   }
	v_mfma_f32_32x32x16_bf16 v[66:81], v[158:161], v[242:245], v[66:81]
	v_mfma_f32_32x32x16_bf16 v[2:17], v[158:161], v[246:249], v[2:17]
	s_cbranch_scc0 .LBB0_170
	s_add_i32 s5, 0, 0x10000
	v_add_u32_e32 v158, s5, v143
	v_add_u32_e32 v159, s5, v149
	v_add_u32_e32 v142, v158, v148
	ds_read_b128 v[134:137], v142 offset:32768
	ds_read_b128 v[150:153], v142 offset:36864
	v_add_u32_e32 v142, v159, v148
	ds_read_b128 v[154:157], v142
	s_mov_b64 s[8:9], 0
	s_waitcnt lgkmcnt(0)
	v_mfma_f32_32x32x16_bf16 v[114:129], v[154:157], v[134:137], v[114:129]
	v_mfma_f32_32x32x16_bf16 v[50:65], v[154:157], v[150:153], v[50:65]
	ds_read_b128 v[154:157], v142 offset:4096
	s_waitcnt lgkmcnt(0)
	v_mfma_f32_32x32x16_bf16 v[98:113], v[154:157], v[134:137], v[98:113]
	v_mfma_f32_32x32x16_bf16 v[34:49], v[154:157], v[150:153], v[34:49]
	ds_read_b128 v[154:157], v142 offset:8192
	s_waitcnt lgkmcnt(0)
	v_mfma_f32_32x32x16_bf16 v[82:97], v[154:157], v[134:137], v[82:97]
	v_mfma_f32_32x32x16_bf16 v[18:33], v[154:157], v[150:153], v[18:33]
	ds_read_b128 v[154:157], v142 offset:12288
	v_add_u32_e32 v142, v158, v141
	v_add_u32_e32 v141, v159, v141
	s_waitcnt lgkmcnt(0)
	v_mfma_f32_32x32x16_bf16 v[66:81], v[154:157], v[134:137], v[66:81]
	v_mfma_f32_32x32x16_bf16 v[2:17], v[154:157], v[150:153], v[2:17]
	ds_read_b128 v[134:137], v142 offset:32768
	ds_read_b128 v[148:151], v142 offset:36864
	ds_read_b128 v[152:155], v141
	s_waitcnt lgkmcnt(0)
	v_mfma_f32_32x32x16_bf16 v[114:129], v[152:155], v[134:137], v[114:129]
	v_mfma_f32_32x32x16_bf16 v[50:65], v[152:155], v[148:151], v[50:65]
	ds_read_b128 v[152:155], v141 offset:4096
	s_waitcnt lgkmcnt(0)
	v_mfma_f32_32x32x16_bf16 v[98:113], v[152:155], v[134:137], v[98:113]
	v_mfma_f32_32x32x16_bf16 v[34:49], v[152:155], v[148:151], v[34:49]
	ds_read_b128 v[152:155], v141 offset:8192
	s_waitcnt lgkmcnt(0)
	v_mfma_f32_32x32x16_bf16 v[82:97], v[152:155], v[134:137], v[82:97]
	v_mfma_f32_32x32x16_bf16 v[18:33], v[152:155], v[148:151], v[18:33]
	ds_read_b128 v[152:155], v141 offset:12288
	v_add_u32_e32 v141, v158, v140
	s_waitcnt lgkmcnt(0)
	v_mfma_f32_32x32x16_bf16 v[66:81], v[152:155], v[134:137], v[66:81]
	v_mfma_f32_32x32x16_bf16 v[2:17], v[152:155], v[148:151], v[2:17]
	v_add_u32_e32 v152, v159, v140
	ds_read_b128 v[134:137], v141 offset:32768
	ds_read_b128 v[148:151], v141 offset:36864
	ds_read_b128 v[140:143], v152
	s_waitcnt lgkmcnt(0)
	v_mfma_f32_32x32x16_bf16 v[114:129], v[140:143], v[134:137], v[114:129]
	v_mfma_f32_32x32x16_bf16 v[50:65], v[140:143], v[148:151], v[50:65]
	ds_read_b128 v[140:143], v152 offset:4096
	s_waitcnt lgkmcnt(0)
	v_mfma_f32_32x32x16_bf16 v[98:113], v[140:143], v[134:137], v[98:113]
	v_mfma_f32_32x32x16_bf16 v[34:49], v[140:143], v[148:151], v[34:49]
	ds_read_b128 v[140:143], v152 offset:8192
	s_waitcnt lgkmcnt(0)
	v_mfma_f32_32x32x16_bf16 v[82:97], v[140:143], v[134:137], v[82:97]
	v_mfma_f32_32x32x16_bf16 v[18:33], v[140:143], v[148:151], v[18:33]
	ds_read_b128 v[140:143], v152 offset:12288
	s_waitcnt lgkmcnt(0)
	v_mfma_f32_32x32x16_bf16 v[66:81], v[140:143], v[134:137], v[66:81]
	v_mfma_f32_32x32x16_bf16 v[2:17], v[140:143], v[148:151], v[2:17]
	v_add_u32_e32 v140, v158, v0
	v_add_u32_e32 v0, v159, v0
	ds_read_b128 v[134:137], v140 offset:32768
	ds_read_b128 v[140:143], v140 offset:36864
	ds_read_b128 v[148:151], v0
	s_waitcnt lgkmcnt(0)
	v_mfma_f32_32x32x16_bf16 v[114:129], v[148:151], v[134:137], v[114:129]
	v_mfma_f32_32x32x16_bf16 v[50:65], v[148:151], v[140:143], v[50:65]
	ds_read_b128 v[148:151], v0 offset:4096
	s_waitcnt lgkmcnt(0)
	v_mfma_f32_32x32x16_bf16 v[98:113], v[148:151], v[134:137], v[98:113]
	v_mfma_f32_32x32x16_bf16 v[34:49], v[148:151], v[140:143], v[34:49]
	ds_read_b128 v[148:151], v0 offset:8192
	s_waitcnt lgkmcnt(0)
	v_mfma_f32_32x32x16_bf16 v[82:97], v[148:151], v[134:137], v[82:97]
	v_mfma_f32_32x32x16_bf16 v[18:33], v[148:151], v[140:143], v[18:33]
	ds_read_b128 v[148:151], v0 offset:12288
	s_waitcnt vmcnt(0) lgkmcnt(0)
	s_barrier
	s_waitcnt lgkmcnt(0)
	v_mfma_f32_32x32x16_bf16 v[66:81], v[148:151], v[134:137], v[66:81]
	v_mfma_f32_32x32x16_bf16 v[2:17], v[148:151], v[140:143], v[2:17]

; DI f32x16 mfma(bf16x8 a, bf16x8 b, f32x16 c) { return __builtin_amdgcn_mfma_f32_32x32x16_bf16(a, b, c, 0, 0, 0); }
;     ...
;   __syncthreads();
;   DMA_ISSUE(0, 0)
;   asm volatile("s_waitcnt vmcnt(0)" ::: "memory");
;   __builtin_amdgcn_s_barrier();
;   for (int kt = 0; kt < nk; ++kt) {
;     const char* cur = lds + (kt & 1) * DBUF;
;     if (kt + 1 < nk) DMA_ISSUE((kt + 1) & 1, kt + 1)
; #pragma unroll(NTB == 1 ? 2 : 4)
;     for (int s = 0; s < 4; ++s) {
;       const int ro = ((2 * s + hh) ^ xr) * 16;
;       bf16x8 bfr[NTB];
; #pragma unroll
;       for (int tb = 0; tb < NTB; ++tb) bfr[tb] = *(const bf16x8*)(cur + bbase + tb * 32 * DROW + ro);
; #pragma unroll
;       for (int fb = 0; fb < NFB; ++fb) {
;         const bf16x8 afr = *(const bf16x8*)(cur + abase + fb * 32 * DROW + ro);
; #pragma unroll
;         for (int tb = 0; tb < NTB; ++tb) acc[tb * NFB + fb] = mfma(afr, bfr[tb], acc[tb * NFB + fb]);
;       }
;     }
;     asm volatile("s_waitcnt vmcnt(0) lgkmcnt(0)" ::: "memory");
;     __builtin_amdgcn_s_barrier();
;   }
.LBB0_174:
	s_add_i32 s8, s5, 0xffff0000
	s_and_b32 s8, s8, 0x10000
	v_add_u32_e32 v184, s8, v143
	v_add_u32_e32 v186, s8, v149
	v_add_u32_e32 v189, v184, v148
	v_add_u32_e32 v194, v186, v148
	ds_read_b128 v[234:237], v189 offset:32768
	ds_read_b128 v[238:241], v189 offset:36864
	ds_read_b128 v[250:253], v194
	ds_read_b128 v[180:183], v194 offset:4096
	ds_read_b128 v[190:193], v194 offset:8192
	ds_read_b128 v[158:161], v194 offset:12288
	v_add_u32_e32 v189, v184, v141
	v_add_u32_e32 v194, v186, v141
	ds_read_b128 v[242:245], v189 offset:32768
	ds_read_b128 v[246:249], v189 offset:36864
	s_waitcnt lgkmcnt(5)
	v_mfma_f32_32x32x16_bf16 v[114:129], v[250:253], v[234:237], v[114:129]
	v_mfma_f32_32x32x16_bf16 v[50:65], v[250:253], v[238:241], v[50:65]
	ds_read_b128 v[250:253], v194
	s_and_b32 s9, s5, 0x10000
	v_add_u32_e32 v154, s9, v142
	v_lshl_add_u64 v[150:151], v[134:135], 0, s[34:35]
	v_readfirstlane_b32 s9, v154
	v_add_u32_e32 v155, 0x2000, v154
	v_lshl_add_u64 v[152:153], v[150:151], 0, s[84:85]
	s_mov_b32 m0, s9
	v_readfirstlane_b32 s9, v155
	v_add_u32_e32 v155, 0x4000, v154
	global_load_lds_dwordx4 v[152:153], off
	v_lshl_add_u64 v[152:153], v[150:151], 0, s[90:91]
	s_mov_b32 m0, s9
	v_readfirstlane_b32 s9, v155
	global_load_lds_dwordx4 v[152:153], off
	s_waitcnt lgkmcnt(5)
	v_mfma_f32_32x32x16_bf16 v[98:113], v[180:183], v[234:237], v[98:113]
	v_mfma_f32_32x32x16_bf16 v[34:49], v[180:183], v[238:241], v[34:49]
	ds_read_b128 v[180:183], v194 offset:4096
	v_lshl_add_u64 v[152:153], v[150:151], 0, s[48:49]
	s_mov_b32 m0, s9
	v_lshl_add_u64 v[150:151], v[150:151], 0, s[50:51]
	global_load_lds_dwordx4 v[152:153], off
	v_add_u32_e32 v152, 0x6000, v154
	v_add_u32_e32 v155, 0x8000, v154
	v_readfirstlane_b32 s9, v152
	s_mov_b32 m0, s9
	v_readfirstlane_b32 s9, v155
	global_load_lds_dwordx4 v[150:151], off
	s_waitcnt lgkmcnt(5)
	v_mfma_f32_32x32x16_bf16 v[82:97], v[190:193], v[234:237], v[82:97]
	v_mfma_f32_32x32x16_bf16 v[18:33], v[190:193], v[238:241], v[18:33]
	ds_read_b128 v[190:193], v194 offset:8192
	v_lshl_add_u64 v[150:151], v[136:137], 0, s[34:35]
	v_add_u32_e32 v155, 0xa000, v154
	v_lshl_add_u64 v[152:153], v[150:151], 0, s[84:85]
	s_mov_b32 m0, s9
	v_readfirstlane_b32 s9, v155
	v_add_u32_e32 v155, 0xc000, v154
	global_load_lds_dwordx4 v[152:153], off
	v_lshl_add_u64 v[152:153], v[150:151], 0, s[90:91]
	s_mov_b32 m0, s9
	v_readfirstlane_b32 s9, v155
	s_add_i32 s8, s5, 0xffff0000
	global_load_lds_dwordx4 v[152:153], off
	s_waitcnt lgkmcnt(5)
	v_mfma_f32_32x32x16_bf16 v[66:81], v[158:161], v[234:237], v[66:81]
	v_mfma_f32_32x32x16_bf16 v[2:17], v[158:161], v[238:241], v[2:17]
	ds_read_b128 v[158:161], v194 offset:12288
	v_lshl_add_u64 v[152:153], v[150:151], 0, s[48:49]
	s_mov_b32 m0, s9
	s_and_b32 s8, s8, 0x10000
	global_load_lds_dwordx4 v[152:153], off
	v_add_u32_e32 v152, 0xe000, v154
	s_add_i32 s8, s8, 0
	v_readfirstlane_b32 s9, v152
	v_lshl_add_u64 v[150:151], v[150:151], 0, s[50:51]
	s_mov_b32 m0, s9
	v_add_u32_e32 v162, s8, v143
	v_add_u32_e32 v163, s8, v149
	global_load_lds_dwordx4 v[150:151], off
	v_add_u32_e32 v189, v184, v140
	v_add_u32_e32 v194, v186, v140
	ds_read_b128 v[234:237], v189 offset:32768
	ds_read_b128 v[238:241], v189 offset:36864
	s_waitcnt lgkmcnt(5)
	v_mfma_f32_32x32x16_bf16 v[114:129], v[250:253], v[242:245], v[114:129]
	v_mfma_f32_32x32x16_bf16 v[50:65], v[250:253], v[246:249], v[50:65]
	ds_read_b128 v[250:253], v194
	s_add_u32 s34, s34, 0x80
	s_addc_u32 s35, s35, 0
	s_add_i32 s5, s5, 0x10000
	s_cmpk_eq_i32 s34, 0x780
	s_waitcnt lgkmcnt(5)
	v_mfma_f32_32x32x16_bf16 v[98:113], v[180:183], v[242:245], v[98:113]
	v_mfma_f32_32x32x16_bf16 v[34:49], v[180:183], v[246:249], v[34:49]
	ds_read_b128 v[180:183], v194 offset:4096
	s_waitcnt lgkmcnt(5)
	v_mfma_f32_32x32x16_bf16 v[82:97], v[190:193], v[242:245], v[82:97]
	v_mfma_f32_32x32x16_bf16 v[18:33], v[190:193], v[246:249], v[18:33]
	ds_read_b128 v[190:193], v194 offset:8192
	s_waitcnt lgkmcnt(5)
	v_mfma_f32_32x32x16_bf16 v[66:81], v[158:161], v[242:245], v[66:81]
	v_mfma_f32_32x32x16_bf16 v[2:17], v[158:161], v[246:249], v[2:17]
	ds_read_b128 v[158:161], v194 offset:12288
	v_add_u32_e32 v189, v184, v0
	v_add_u32_e32 v194, v186, v0
	ds_read_b128 v[242:245], v189 offset:32768
	ds_read_b128 v[246:249], v189 offset:36864
	s_waitcnt lgkmcnt(5)
	v_mfma_f32_32x32x16_bf16 v[114:129], v[250:253], v[234:237], v[114:129]
	v_mfma_f32_32x32x16_bf16 v[50:65], v[250:253], v[238:241], v[50:65]
	ds_read_b128 v[250:253], v194
	s_waitcnt lgkmcnt(5)
	v_mfma_f32_32x32x16_bf16 v[98:113], v[180:183], v[234:237], v[98:113]
	v_mfma_f32_32x32x16_bf16 v[34:49], v[180:183], v[238:241], v[34:49]
	ds_read_b128 v[180:183], v194 offset:4096
	s_waitcnt lgkmcnt(5)
	v_mfma_f32_32x32x16_bf16 v[82:97], v[190:193], v[234:237], v[82:97]
	v_mfma_f32_32x32x16_bf16 v[18:33], v[190:193], v[238:241], v[18:33]
	ds_read_b128 v[190:193], v194 offset:8192
	s_waitcnt lgkmcnt(5)
	v_mfma_f32_32x32x16_bf16 v[66:81], v[158:161], v[234:237], v[66:81]
	v_mfma_f32_32x32x16_bf16 v[2:17], v[158:161], v[238:241], v[2:17]
	ds_read_b128 v[158:161], v194 offset:12288
	s_waitcnt lgkmcnt(3)
	v_mfma_f32_32x32x16_bf16 v[114:129], v[250:253], v[242:245], v[114:129]
	v_mfma_f32_32x32x16_bf16 v[50:65], v[250:253], v[246:249], v[50:65]
	s_waitcnt lgkmcnt(2)
	v_mfma_f32_32x32x16_bf16 v[98:113], v[180:183], v[242:245], v[98:113]
	v_mfma_f32_32x32x16_bf16 v[34:49], v[180:183], v[246:249], v[34:49]
	s_waitcnt lgkmcnt(1)
	v_mfma_f32_32x32x16_bf16 v[82:97], v[190:193], v[242:245], v[82:97]
	v_mfma_f32_32x32x16_bf16 v[18:33], v[190:193], v[246:249], v[18:33]
	s_waitcnt vmcnt(0) lgkmcnt(0)
	s_barrier
; DI f32x16 mfma(bf16x8 a, bf16x8 b, f32x16 c) { return __builtin_amdgcn_mfma_f32_32x32x16_bf16(a, b, c, 0, 0, 0); }
;     ...
;   for (int kt = 0; kt < nk; ++kt) {
;     const char* cur = lds + (kt & 1) * DBUF;
;     if (kt + 1 < nk) DMA_ISSUE((kt + 1) & 1, kt + 1)
; #pragma unroll(NTB == 1 ? 2 : 4)
;     for (int s = 0; s < 4; ++s) {
;       const int ro = ((2 * s + hh) ^ xr) * 16;
;       bf16x8 bfr[NTB];
; #pragma unroll
;       for (int tb = 0; tb < NTB; ++tb) bfr[tb] = *(const bf16x8*)(cur + bbase + tb * 32 * DROW + ro);
; #pragma unroll
;       for (int fb = 0; fb < NFB; ++fb) {
;         const bf16x8 afr = *(const bf16x8*)(cur + abase + fb * 32 * DROW + ro);
; #pragma unroll
;         for (int tb = 0; tb < NTB; ++tb) acc[tb * NFB + fb] = mfma(afr, bfr[tb], acc[tb * NFB + fb]);
;       }
;     }
;     asm volatile("s_waitcnt vmcnt(0) lgkmcnt(0)" ::: "memory");
;     __builtin_amdgcn_s_barrier();
;   }
	v_mfma_f32_32x32x16_bf16 v[66:81], v[158:161], v[242:245], v[66:81]
	v_mfma_f32_32x32x16_bf16 v[2:17], v[158:161], v[246:249], v[2:17]
	s_cbranch_scc0 .LBB0_174
	s_add_i32 s5, 0, 0x10000
	v_add_u32_e32 v158, s5, v143
	v_add_u32_e32 v159, s5, v149
	v_add_u32_e32 v142, v158, v148
	ds_read_b128 v[134:137], v142 offset:32768
	ds_read_b128 v[150:153], v142 offset:36864
	v_add_u32_e32 v142, v159, v148
	ds_read_b128 v[154:157], v142
	s_waitcnt lgkmcnt(0)
	v_mfma_f32_32x32x16_bf16 v[114:129], v[154:157], v[134:137], v[114:129]
	v_mfma_f32_32x32x16_bf16 v[50:65], v[154:157], v[150:153], v[50:65]
	ds_read_b128 v[154:157], v142 offset:4096
	s_waitcnt lgkmcnt(0)
	v_mfma_f32_32x32x16_bf16 v[98:113], v[154:157], v[134:137], v[98:113]
	v_mfma_f32_32x32x16_bf16 v[34:49], v[154:157], v[150:153], v[34:49]
	ds_read_b128 v[154:157], v142 offset:8192
	s_waitcnt lgkmcnt(0)
	v_mfma_f32_32x32x16_bf16 v[82:97], v[154:157], v[134:137], v[82:97]
	v_mfma_f32_32x32x16_bf16 v[18:33], v[154:157], v[150:153], v[18:33]
	ds_read_b128 v[154:157], v142 offset:12288
	v_add_u32_e32 v142, v158, v141
	v_add_u32_e32 v141, v159, v141
	s_waitcnt lgkmcnt(0)
	v_mfma_f32_32x32x16_bf16 v[66:81], v[154:157], v[134:137], v[66:81]
	v_mfma_f32_32x32x16_bf16 v[2:17], v[154:157], v[150:153], v[2:17]
	ds_read_b128 v[134:137], v142 offset:32768
	ds_read_b128 v[148:151], v142 offset:36864
	ds_read_b128 v[152:155], v141
	s_waitcnt lgkmcnt(0)
	v_mfma_f32_32x32x16_bf16 v[114:129], v[152:155], v[134:137], v[114:129]
	v_mfma_f32_32x32x16_bf16 v[50:65], v[152:155], v[148:151], v[50:65]
	ds_read_b128 v[152:155], v141 offset:4096
	s_waitcnt lgkmcnt(0)
	v_mfma_f32_32x32x16_bf16 v[98:113], v[152:155], v[134:137], v[98:113]
	v_mfma_f32_32x32x16_bf16 v[34:49], v[152:155], v[148:151], v[34:49]
	ds_read_b128 v[152:155], v141 offset:8192
	s_waitcnt lgkmcnt(0)
	v_mfma_f32_32x32x16_bf16 v[82:97], v[152:155], v[134:137], v[82:97]
	v_mfma_f32_32x32x16_bf16 v[18:33], v[152:155], v[148:151], v[18:33]
	ds_read_b128 v[152:155], v141 offset:12288
	v_add_u32_e32 v141, v158, v140
	s_waitcnt lgkmcnt(0)
	v_mfma_f32_32x32x16_bf16 v[66:81], v[152:155], v[134:137], v[66:81]
	v_mfma_f32_32x32x16_bf16 v[2:17], v[152:155], v[148:151], v[2:17]
	v_add_u32_e32 v152, v159, v140
	ds_read_b128 v[134:137], v141 offset:32768
	ds_read_b128 v[148:151], v141 offset:36864
	ds_read_b128 v[140:143], v152
	s_waitcnt lgkmcnt(0)
	v_mfma_f32_32x32x16_bf16 v[114:129], v[140:143], v[134:137], v[114:129]
	v_mfma_f32_32x32x16_bf16 v[50:65], v[140:143], v[148:151], v[50:65]
	ds_read_b128 v[140:143], v152 offset:4096
	s_waitcnt lgkmcnt(0)
	v_mfma_f32_32x32x16_bf16 v[98:113], v[140:143], v[134:137], v[98:113]
	v_mfma_f32_32x32x16_bf16 v[34:49], v[140:143], v[148:151], v[34:49]
	ds_read_b128 v[140:143], v152 offset:8192
	s_waitcnt lgkmcnt(0)
	v_mfma_f32_32x32x16_bf16 v[82:97], v[140:143], v[134:137], v[82:97]
	v_mfma_f32_32x32x16_bf16 v[18:33], v[140:143], v[148:151], v[18:33]
	ds_read_b128 v[140:143], v152 offset:12288
	s_waitcnt lgkmcnt(0)
	v_mfma_f32_32x32x16_bf16 v[66:81], v[140:143], v[134:137], v[66:81]
	v_mfma_f32_32x32x16_bf16 v[2:17], v[140:143], v[148:151], v[2:17]
	v_add_u32_e32 v140, v158, v0
	v_add_u32_e32 v0, v159, v0
	ds_read_b128 v[134:137], v140 offset:32768
	ds_read_b128 v[140:143], v140 offset:36864
	ds_read_b128 v[148:151], v0
	s_waitcnt lgkmcnt(0)
	v_mfma_f32_32x32x16_bf16 v[114:129], v[148:151], v[134:137], v[114:129]
	v_mfma_f32_32x32x16_bf16 v[50:65], v[148:151], v[140:143], v[50:65]
	ds_read_b128 v[148:151], v0 offset:4096
	s_waitcnt lgkmcnt(0)
	v_mfma_f32_32x32x16_bf16 v[98:113], v[148:151], v[134:137], v[98:113]
	v_mfma_f32_32x32x16_bf16 v[34:49], v[148:151], v[140:143], v[34:49]
	ds_read_b128 v[148:151], v0 offset:8192
	s_waitcnt lgkmcnt(0)
	v_mfma_f32_32x32x16_bf16 v[82:97], v[148:151], v[134:137], v[82:97]
	v_mfma_f32_32x32x16_bf16 v[18:33], v[148:151], v[140:143], v[18:33]
	ds_read_b128 v[148:151], v0 offset:12288
	s_waitcnt vmcnt(0) lgkmcnt(0)
	s_barrier
	s_waitcnt lgkmcnt(0)
	v_mfma_f32_32x32x16_bf16 v[66:81], v[148:151], v[134:137], v[66:81]
	v_mfma_f32_32x32x16_bf16 v[2:17], v[148:151], v[140:143], v[2:17]

; DI f32x16 mfma(bf16x8 a, bf16x8 b, f32x16 c) { return __builtin_amdgcn_mfma_f32_32x32x16_bf16(a, b, c, 0, 0, 0); }
;     ...
;   __syncthreads();
;   DMA_ISSUE(0, 0)
;   asm volatile("s_waitcnt vmcnt(0)" ::: "memory");
;   __builtin_amdgcn_s_barrier();
;   for (int kt = 0; kt < nk; ++kt) {
;     const char* cur = lds + (kt & 1) * DBUF;
;     if (kt + 1 < nk) DMA_ISSUE((kt + 1) & 1, kt + 1)
; #pragma unroll(NTB == 1 ? 2 : 4)
;     for (int s = 0; s < 4; ++s) {
;       const int ro = ((2 * s + hh) ^ xr) * 16;
;       bf16x8 bfr[NTB];
; #pragma unroll
;       for (int tb = 0; tb < NTB; ++tb) bfr[tb] = *(const bf16x8*)(cur + bbase + tb * 32 * DROW + ro);
; #pragma unroll
;       for (int fb = 0; fb < NFB; ++fb) {
;         const bf16x8 afr = *(const bf16x8*)(cur + abase + fb * 32 * DROW + ro);
; #pragma unroll
;         for (int tb = 0; tb < NTB; ++tb) acc[tb * NFB + fb] = mfma(afr, bfr[tb], acc[tb * NFB + fb]);
;       }
;     }
;     asm volatile("s_waitcnt vmcnt(0) lgkmcnt(0)" ::: "memory");
;     __builtin_amdgcn_s_barrier();
;   }
.LBB0_194:
	s_add_i32 s8, s1, 0xffff0000
	s_and_b32 s8, s8, 0x10000
	v_add_u32_e32 v184, s8, v137
	v_add_u32_e32 v186, s8, v139
	v_add_u32_e32 v189, v184, v138
	v_add_u32_e32 v194, v186, v138
	ds_read_b128 v[234:237], v189 offset:32768
	ds_read_b128 v[238:241], v189 offset:36864
	ds_read_b128 v[250:253], v194
	ds_read_b128 v[180:183], v194 offset:4096
	ds_read_b128 v[190:193], v194 offset:8192
	ds_read_b128 v[152:155], v194 offset:12288
	v_add_u32_e32 v189, v184, v135
	v_add_u32_e32 v194, v186, v135
	ds_read_b128 v[242:245], v189 offset:32768
	ds_read_b128 v[246:249], v189 offset:36864
	s_waitcnt lgkmcnt(5)
	v_mfma_f32_32x32x16_bf16 v[114:129], v[250:253], v[234:237], v[114:129]
	v_mfma_f32_32x32x16_bf16 v[50:65], v[250:253], v[238:241], v[50:65]
	ds_read_b128 v[250:253], v194
	s_and_b32 s9, s1, 0x10000
	v_add_u32_e32 v148, s9, v136
	v_lshl_add_u64 v[140:141], v[130:131], 0, s[4:5]
	s_mov_b64 s[10:11], 0xc90080
	v_readfirstlane_b32 s9, v148
	v_add_u32_e32 v149, 0x2000, v148
	v_lshl_add_u64 v[142:143], v[140:141], 0, s[10:11]
	s_mov_b32 m0, s9
	s_mov_b64 s[10:11], 0xcb0080
	v_readfirstlane_b32 s9, v149
	v_add_u32_e32 v149, 0x4000, v148
	global_load_lds_dwordx4 v[142:143], off
	v_lshl_add_u64 v[142:143], v[140:141], 0, s[10:11]
	s_mov_b32 m0, s9
	s_mov_b64 s[10:11], 0xcd0080
	v_readfirstlane_b32 s9, v149
	global_load_lds_dwordx4 v[142:143], off
	s_waitcnt lgkmcnt(5)
	v_mfma_f32_32x32x16_bf16 v[98:113], v[180:183], v[234:237], v[98:113]
	v_mfma_f32_32x32x16_bf16 v[34:49], v[180:183], v[238:241], v[34:49]
	ds_read_b128 v[180:183], v194 offset:4096
	v_lshl_add_u64 v[142:143], v[140:141], 0, s[10:11]
	s_mov_b32 m0, s9
	s_mov_b64 s[10:11], 0xcf0080
	global_load_lds_dwordx4 v[142:143], off
	v_add_u32_e32 v142, 0x6000, v148
	v_lshl_add_u64 v[140:141], v[140:141], 0, s[10:11]
	v_readfirstlane_b32 s9, v142
	s_mov_b32 m0, s9
	v_add_u32_e32 v149, 0x8000, v148
	global_load_lds_dwordx4 v[140:141], off
	s_waitcnt lgkmcnt(5)
	v_mfma_f32_32x32x16_bf16 v[82:97], v[190:193], v[234:237], v[82:97]
	v_mfma_f32_32x32x16_bf16 v[18:33], v[190:193], v[238:241], v[18:33]
	ds_read_b128 v[190:193], v194 offset:8192
	v_lshl_add_u64 v[140:141], v[132:133], 0, s[4:5]
	s_mov_b64 s[10:11], 0x6390080
	v_readfirstlane_b32 s9, v149
	v_add_u32_e32 v149, 0xa000, v148
	v_lshl_add_u64 v[142:143], v[140:141], 0, s[10:11]
	s_mov_b32 m0, s9
	s_mov_b64 s[10:11], 0x63b0080
	v_readfirstlane_b32 s9, v149
	v_add_u32_e32 v149, 0xc000, v148
	global_load_lds_dwordx4 v[142:143], off
	v_lshl_add_u64 v[142:143], v[140:141], 0, s[10:11]
	s_mov_b32 m0, s9
	s_mov_b64 s[10:11], 0x63d0080
	v_readfirstlane_b32 s9, v149
	s_add_i32 s8, s1, 0xffff0000
	global_load_lds_dwordx4 v[142:143], off
	s_waitcnt lgkmcnt(5)
	v_mfma_f32_32x32x16_bf16 v[66:81], v[152:155], v[234:237], v[66:81]
	v_mfma_f32_32x32x16_bf16 v[2:17], v[152:155], v[238:241], v[2:17]
	ds_read_b128 v[152:155], v194 offset:12288
	v_lshl_add_u64 v[142:143], v[140:141], 0, s[10:11]
	s_mov_b32 m0, s9
	s_and_b32 s8, s8, 0x10000
	global_load_lds_dwordx4 v[142:143], off
	v_add_u32_e32 v142, 0xe000, v148
	s_add_i32 s8, s8, 0
	s_mov_b64 s[10:11], 0x63f0080
	v_readfirstlane_b32 s9, v142
	v_lshl_add_u64 v[140:141], v[140:141], 0, s[10:11]
	s_mov_b32 m0, s9
	v_add_u32_e32 v156, s8, v137
	v_add_u32_e32 v157, s8, v139
	global_load_lds_dwordx4 v[140:141], off
	v_add_u32_e32 v189, v184, v134
	v_add_u32_e32 v194, v186, v134
	ds_read_b128 v[234:237], v189 offset:32768
	ds_read_b128 v[238:241], v189 offset:36864
	s_waitcnt lgkmcnt(5)
	v_mfma_f32_32x32x16_bf16 v[114:129], v[250:253], v[242:245], v[114:129]
	v_mfma_f32_32x32x16_bf16 v[50:65], v[250:253], v[246:249], v[50:65]
	ds_read_b128 v[250:253], v194
	s_add_u32 s4, s4, 0x80
	s_addc_u32 s5, s5, 0
	s_add_i32 s1, s1, 0x10000
	s_cmpk_eq_i32 s4, 0x780
	s_waitcnt lgkmcnt(5)
	v_mfma_f32_32x32x16_bf16 v[98:113], v[180:183], v[242:245], v[98:113]
	v_mfma_f32_32x32x16_bf16 v[34:49], v[180:183], v[246:249], v[34:49]
	ds_read_b128 v[180:183], v194 offset:4096
	s_waitcnt lgkmcnt(5)
	v_mfma_f32_32x32x16_bf16 v[82:97], v[190:193], v[242:245], v[82:97]
	v_mfma_f32_32x32x16_bf16 v[18:33], v[190:193], v[246:249], v[18:33]
	ds_read_b128 v[190:193], v194 offset:8192
	s_waitcnt lgkmcnt(5)
	v_mfma_f32_32x32x16_bf16 v[66:81], v[152:155], v[242:245], v[66:81]
	v_mfma_f32_32x32x16_bf16 v[2:17], v[152:155], v[246:249], v[2:17]
	ds_read_b128 v[152:155], v194 offset:12288
	v_add_u32_e32 v189, v184, v0
	v_add_u32_e32 v194, v186, v0
	ds_read_b128 v[242:245], v189 offset:32768
	ds_read_b128 v[246:249], v189 offset:36864
	s_waitcnt lgkmcnt(5)
	v_mfma_f32_32x32x16_bf16 v[114:129], v[250:253], v[234:237], v[114:129]
	v_mfma_f32_32x32x16_bf16 v[50:65], v[250:253], v[238:241], v[50:65]
	ds_read_b128 v[250:253], v194
	s_waitcnt lgkmcnt(5)
	v_mfma_f32_32x32x16_bf16 v[98:113], v[180:183], v[234:237], v[98:113]
	v_mfma_f32_32x32x16_bf16 v[34:49], v[180:183], v[238:241], v[34:49]
	ds_read_b128 v[180:183], v194 offset:4096
	s_waitcnt lgkmcnt(5)
	v_mfma_f32_32x32x16_bf16 v[82:97], v[190:193], v[234:237], v[82:97]
	v_mfma_f32_32x32x16_bf16 v[18:33], v[190:193], v[238:241], v[18:33]
	ds_read_b128 v[190:193], v194 offset:8192
	s_waitcnt lgkmcnt(5)
	v_mfma_f32_32x32x16_bf16 v[66:81], v[152:155], v[234:237], v[66:81]
	v_mfma_f32_32x32x16_bf16 v[2:17], v[152:155], v[238:241], v[2:17]
	ds_read_b128 v[152:155], v194 offset:12288
	s_waitcnt lgkmcnt(3)
	v_mfma_f32_32x32x16_bf16 v[114:129], v[250:253], v[242:245], v[114:129]
	v_mfma_f32_32x32x16_bf16 v[50:65], v[250:253], v[246:249], v[50:65]
	s_waitcnt lgkmcnt(2)
	v_mfma_f32_32x32x16_bf16 v[98:113], v[180:183], v[242:245], v[98:113]
	v_mfma_f32_32x32x16_bf16 v[34:49], v[180:183], v[246:249], v[34:49]
	s_waitcnt lgkmcnt(1)
	v_mfma_f32_32x32x16_bf16 v[82:97], v[190:193], v[242:245], v[82:97]
	v_mfma_f32_32x32x16_bf16 v[18:33], v[190:193], v[246:249], v[18:33]
	s_waitcnt vmcnt(0) lgkmcnt(0)
	s_barrier
; DI int get_tid() { int t = threadIdx.x; asm volatile("" : "+v"(t)); return t; }
; DI char* get_ws(const Params& p) { char* w = p.ws; asm volatile("" : "+s"(w)); return w; }
; DI float xsum32(float v) { const auto r = __builtin_amdgcn_permlane32_swap(__float_as_uint(v), __float_as_uint(v), false, false); return __uint_as_float(r[0]) + __uint_as_float(r[1]); }
; DI f32x16 mfma(bf16x8 a, bf16x8 b, f32x16 c) { return __builtin_amdgcn_mfma_f32_32x32x16_bf16(a, b, c, 0, 0, 0); }
; DI int perm16(int s) { return (s & ~12) | ((s & 4) << 1) | ((s & 8) >> 1); }
;     ...
;   for (int kt = 0; kt < nk; ++kt) {
;     const char* cur = lds + (kt & 1) * DBUF;
;     if (kt + 1 < nk) DMA_ISSUE((kt + 1) & 1, kt + 1)
; #pragma unroll(NTB == 1 ? 2 : 4)
;     for (int s = 0; s < 4; ++s) {
;       const int ro = ((2 * s + hh) ^ xr) * 16;
;       bf16x8 bfr[NTB];
; #pragma unroll
;       for (int tb = 0; tb < NTB; ++tb) bfr[tb] = *(const bf16x8*)(cur + bbase + tb * 32 * DROW + ro);
; #pragma unroll
;       for (int fb = 0; fb < NFB; ++fb) {
;         const bf16x8 afr = *(const bf16x8*)(cur + abase + fb * 32 * DROW + ro);
; #pragma unroll
;         for (int tb = 0; tb < NTB; ++tb) acc[tb * NFB + fb] = mfma(afr, bfr[tb], acc[tb * NFB + fb]);
;       }
;     }
;     asm volatile("s_waitcnt vmcnt(0) lgkmcnt(0)" ::: "memory");
;     __builtin_amdgcn_s_barrier();
;   }
; DI void memkv_epilogue(const Params& p, int l, int mt, int ft, f32x16* acc) {
;   char* ws = get_ws(p);
;   const int tid_ = get_tid(); const int lane = tid_ & 63, wave = tid_ >> 6, l32 = lane & 31, hh = lane >> 5;
;   const int b = mt >> 8, m = mt & 255;
;   if (ft < 4) {
;     const int head = ft;
;     float ss = sumsq16(acc[0]) + sumsq16(acc[1]) + sumsq16(acc[2]) + sumsq16(acc[3]);
;     ss = xsum32(ss);
;     const float rstd = rsqrtf(ss * (1.f / 128.f) + EPS);
;     const float* g = p.g_mem_k + l * 128;
;     u16* dst = (u16*)(ws + R_KM) + ((size_t)(b * 4 + head) * 256 + m) * 128;
; #pragma unroll
;     for (int fb = 0; fb < 4; ++fb) st_blk_scaled(dst + fb * 32, hh, acc[fb], rstd, g + fb * 32);
;   } else {
;     const int head = ft - 4;
;     u16* dst = (u16*)(ws + R_VM) + ((size_t)(b * 4 + head) * 128) * 256 + perm16(m);
	v_mfma_f32_32x32x16_bf16 v[66:81], v[152:155], v[242:245], v[66:81]
	v_mfma_f32_32x32x16_bf16 v[2:17], v[152:155], v[246:249], v[2:17]
	s_cbranch_scc0 .LBB0_194
	s_add_i32 s1, 0, 0x10000
	v_add_u32_e32 v148, s1, v137
	v_add_u32_e32 v149, s1, v139
	v_add_u32_e32 v136, v148, v138
	v_add_u32_e32 v150, v149, v138
	ds_read_b128 v[130:133], v136 offset:32768
	ds_read_b128 v[140:143], v136 offset:36864
	ds_read_b128 v[136:139], v150
	s_and_b32 s4, s6, -4
	s_waitcnt lgkmcnt(0)
	v_mfma_f32_32x32x16_bf16 v[114:129], v[136:139], v[130:133], v[114:129]
	v_mfma_f32_32x32x16_bf16 v[50:65], v[136:139], v[140:143], v[50:65]
	ds_read_b128 v[136:139], v150 offset:4096
	s_waitcnt lgkmcnt(0)
	v_mfma_f32_32x32x16_bf16 v[98:113], v[136:139], v[130:133], v[98:113]
	v_mfma_f32_32x32x16_bf16 v[34:49], v[136:139], v[140:143], v[34:49]
	ds_read_b128 v[136:139], v150 offset:8192
	s_waitcnt lgkmcnt(0)
	v_mfma_f32_32x32x16_bf16 v[82:97], v[136:139], v[130:133], v[82:97]
	v_mfma_f32_32x32x16_bf16 v[18:33], v[136:139], v[140:143], v[18:33]
	ds_read_b128 v[136:139], v150 offset:12288
	s_waitcnt lgkmcnt(0)
	v_mfma_f32_32x32x16_bf16 v[66:81], v[136:139], v[130:133], v[66:81]
	v_mfma_f32_32x32x16_bf16 v[2:17], v[136:139], v[140:143], v[2:17]
	v_add_u32_e32 v136, v148, v135
	v_add_u32_e32 v135, v149, v135
	ds_read_b128 v[130:133], v136 offset:32768
	ds_read_b128 v[136:139], v136 offset:36864
	ds_read_b128 v[140:143], v135
	s_waitcnt lgkmcnt(0)
	v_mfma_f32_32x32x16_bf16 v[114:129], v[140:143], v[130:133], v[114:129]
	v_mfma_f32_32x32x16_bf16 v[50:65], v[140:143], v[136:139], v[50:65]
	ds_read_b128 v[140:143], v135 offset:4096
	s_waitcnt lgkmcnt(0)
	v_mfma_f32_32x32x16_bf16 v[98:113], v[140:143], v[130:133], v[98:113]
	v_mfma_f32_32x32x16_bf16 v[34:49], v[140:143], v[136:139], v[34:49]
	ds_read_b128 v[140:143], v135 offset:8192
	s_waitcnt lgkmcnt(0)
	v_mfma_f32_32x32x16_bf16 v[82:97], v[140:143], v[130:133], v[82:97]
	v_mfma_f32_32x32x16_bf16 v[18:33], v[140:143], v[136:139], v[18:33]
	ds_read_b128 v[140:143], v135 offset:12288
	v_add_u32_e32 v135, v148, v134
	v_add_u32_e32 v134, v149, v134
	s_waitcnt lgkmcnt(0)
	v_mfma_f32_32x32x16_bf16 v[66:81], v[140:143], v[130:133], v[66:81]
	v_mfma_f32_32x32x16_bf16 v[2:17], v[140:143], v[136:139], v[2:17]
	ds_read_b128 v[130:133], v135 offset:32768
	ds_read_b128 v[136:139], v135 offset:36864
	ds_read_b128 v[140:143], v134
	s_waitcnt lgkmcnt(0)
	v_mfma_f32_32x32x16_bf16 v[114:129], v[140:143], v[130:133], v[114:129]
	v_mfma_f32_32x32x16_bf16 v[50:65], v[140:143], v[136:139], v[50:65]
	ds_read_b128 v[140:143], v134 offset:4096
	s_waitcnt lgkmcnt(0)
	v_mfma_f32_32x32x16_bf16 v[98:113], v[140:143], v[130:133], v[98:113]
	v_mfma_f32_32x32x16_bf16 v[34:49], v[140:143], v[136:139], v[34:49]
	ds_read_b128 v[140:143], v134 offset:8192
	s_waitcnt lgkmcnt(0)
	v_mfma_f32_32x32x16_bf16 v[82:97], v[140:143], v[130:133], v[82:97]
	v_mfma_f32_32x32x16_bf16 v[18:33], v[140:143], v[136:139], v[18:33]
	ds_read_b128 v[140:143], v134 offset:12288
	v_add_u32_e32 v134, v148, v0
	v_add_u32_e32 v0, v149, v0
	s_waitcnt lgkmcnt(0)
	v_mfma_f32_32x32x16_bf16 v[66:81], v[140:143], v[130:133], v[66:81]
	v_mfma_f32_32x32x16_bf16 v[2:17], v[140:143], v[136:139], v[2:17]
	ds_read_b128 v[130:133], v134 offset:32768
	ds_read_b128 v[134:137], v134 offset:36864
	ds_read_b128 v[138:141], v0
	s_waitcnt lgkmcnt(0)
	v_mfma_f32_32x32x16_bf16 v[114:129], v[138:141], v[130:133], v[114:129]
	v_mfma_f32_32x32x16_bf16 v[50:65], v[138:141], v[134:137], v[50:65]
	ds_read_b128 v[138:141], v0 offset:4096
	s_waitcnt lgkmcnt(0)
	v_mfma_f32_32x32x16_bf16 v[98:113], v[138:141], v[130:133], v[98:113]
	v_mfma_f32_32x32x16_bf16 v[34:49], v[138:141], v[134:137], v[34:49]
	ds_read_b128 v[138:141], v0 offset:8192
	s_waitcnt lgkmcnt(0)
	v_mfma_f32_32x32x16_bf16 v[82:97], v[138:141], v[130:133], v[82:97]
	v_mfma_f32_32x32x16_bf16 v[18:33], v[138:141], v[134:137], v[18:33]
	ds_read_b128 v[138:141], v0 offset:12288
	v_lshl_add_u32 v0, s7, 1, v146
	s_mov_b64 s[6:7], s[30:31]
	s_waitcnt vmcnt(0) lgkmcnt(0)
	s_barrier
	s_waitcnt lgkmcnt(0)
	v_mfma_f32_32x32x16_bf16 v[66:81], v[138:141], v[130:133], v[66:81]
	v_add_u32_e32 v130, s4, v0
	v_lshl_or_b32 v131, s0, 8, v231
	v_cmp_lt_i32_e64 s[0:1], 3, v0
	v_add_u32_e32 v0, -4, v130
	v_lshlrev_b64 v[132:133], 16, v[0:1]
	v_mov_b32_e32 v0, v145
	v_mfma_f32_32x32x16_bf16 v[2:17], v[138:141], v[134:137], v[2:17]
	v_bfe_u32 v136, v0, 5, 1
	v_lshlrev_b32_e32 v0, 1, v131
	v_or_b32_e32 v148, v131, v168
	v_and_b32_e32 v135, 8, v0
	s_and_saveexec_b64 s[4:5], s[0:1]
	s_xor_b64 s[4:5], exec, s[4:5]
	s_cbranch_execz .LBB0_197
; DI u16 tobf(float a) { return (u16)(pack2(a, 0.f) & 0xffffu); }
; DI int perm16(int s) { return (s & ~12) | ((s & 4) << 1) | ((s & 8) >> 1); }
; DI void memkv_epilogue(const Params& p, int l, int mt, int ft, f32x16* acc) {
;     ...
;   } else {
;     const int head = ft - 4;
;     u16* dst = (u16*)(ws + R_VM) + ((size_t)(b * 4 + head) * 128) * 256 + perm16(m);
; #pragma unroll
;     for (int fb = 0; fb < 4; ++fb)
; #pragma unroll
;       for (int i = 0; i < 16; ++i) {
;         const int d = fb * 32 + 8 * (i >> 2) + 4 * hh + (i & 3);
;         dst[(size_t)d * 256] = tobf(acc[fb][i]);
;       }
;   }
	v_and_b32_e32 v0, 0xd3, v148
	v_or3_b32 v0, v0, v135, v169
	v_lshl_add_u64 v[138:139], s[6:7], 0, v[132:133]
	v_lshlrev_b32_e32 v0, 1, v0
	v_lshl_add_u64 v[138:139], v[138:139], 0, v[0:1]
	v_lshlrev_b32_e32 v0, 11, v136
	v_lshl_add_u64 v[136:137], v[138:139], 0, v[0:1]
	s_mov_b64 s[2:3], 0x19bb1000
	v_lshl_add_u64 v[138:139], v[136:137], 0, s[2:3]
	v_add_co_u32_e32 v140, vcc, 0x19bb1000, v136
	v_cvt_pk_bf16_f32 v0, v115, s0
	v_cvt_pk_bf16_f32 v114, v114, s0
	v_addc_co_u32_e32 v141, vcc, 0, v137, vcc
	flat_store_short v[138:139], v0 offset:512
	v_cvt_pk_bf16_f32 v0, v116, s0
	s_mov_b32 s2, 0x19bb2000
	flat_store_short v[140:141], v114
	flat_store_short v[138:139], v0 offset:1024
	v_cvt_pk_bf16_f32 v0, v117, s0
	v_add_co_u32_e32 v114, vcc, s2, v136
	flat_store_short v[138:139], v0 offset:1536
	v_cvt_pk_bf16_f32 v0, v118, s0
	v_addc_co_u32_e32 v115, vcc, 0, v137, vcc
	flat_store_short v[114:115], v0
	v_cvt_pk_bf16_f32 v0, v119, s0
	flat_store_short v[114:115], v0 offset:512
	v_cvt_pk_bf16_f32 v0, v120, s0
	flat_store_short v[114:115], v0 offset:1024
	v_cvt_pk_bf16_f32 v0, v121, s0
	s_mov_b32 s2, 0x19bb3000
	flat_store_short v[114:115], v0 offset:1536
	v_add_co_u32_e32 v114, vcc, s2, v136
	v_cvt_pk_bf16_f32 v0, v122, s0
	s_nop 0
	v_addc_co_u32_e32 v115, vcc, 0, v137, vcc
	flat_store_short v[114:115], v0
	v_cvt_pk_bf16_f32 v0, v123, s0
	flat_store_short v[114:115], v0 offset:512
	v_cvt_pk_bf16_f32 v0, v124, s0
	flat_store_short v[114:115], v0 offset:1024
	v_cvt_pk_bf16_f32 v0, v125, s0
	s_mov_b32 s2, 0x19bb4000
	flat_store_short v[114:115], v0 offset:1536
	v_add_co_u32_e32 v114, vcc, s2, v136
	v_cvt_pk_bf16_f32 v0, v126, s0
	s_nop 0
	v_addc_co_u32_e32 v115, vcc, 0, v137, vcc
	flat_store_short v[114:115], v0
	v_cvt_pk_bf16_f32 v0, v127, s0
	flat_store_short v[114:115], v0 offset:512
	v_cvt_pk_bf16_f32 v0, v128, s0
	flat_store_short v[114:115], v0 offset:1024
	v_cvt_pk_bf16_f32 v0, v129, s0
	s_mov_b32 s2, 0x19bb5000
	flat_store_short v[114:115], v0 offset:1536
	v_add_co_u32_e32 v114, vcc, s2, v136
	v_cvt_pk_bf16_f32 v0, v98, s0
	s_nop 0
	v_addc_co_u32_e32 v115, vcc, 0, v137, vcc
	flat_store_short v[114:115], v0
	v_cvt_pk_bf16_f32 v0, v99, s0
	flat_store_short v[114:115], v0 offset:512
	v_cvt_pk_bf16_f32 v0, v100, s0
	s_mov_b32 s2, 0x19bb6000
	flat_store_short v[114:115], v0 offset:1024
	v_cvt_pk_bf16_f32 v0, v101, s0
	v_add_co_u32_e32 v98, vcc, s2, v136
	flat_store_short v[114:115], v0 offset:1536
	v_cvt_pk_bf16_f32 v0, v102, s0
	v_addc_co_u32_e32 v99, vcc, 0, v137, vcc
	flat_store_short v[98:99], v0
	v_cvt_pk_bf16_f32 v0, v103, s0
	flat_store_short v[98:99], v0 offset:512
	v_cvt_pk_bf16_f32 v0, v104, s0
	flat_store_short v[98:99], v0 offset:1024
	v_cvt_pk_bf16_f32 v0, v105, s0
	s_mov_b32 s2, 0x19bb7000
	flat_store_short v[98:99], v0 offset:1536
	v_add_co_u32_e32 v98, vcc, s2, v136
	v_cvt_pk_bf16_f32 v0, v106, s0
	s_nop 0
	v_addc_co_u32_e32 v99, vcc, 0, v137, vcc
	flat_store_short v[98:99], v0
	v_cvt_pk_bf16_f32 v0, v107, s0
	flat_store_short v[98:99], v0 offset:512
	v_cvt_pk_bf16_f32 v0, v108, s0
	flat_store_short v[98:99], v0 offset:1024
	v_cvt_pk_bf16_f32 v0, v109, s0
	s_mov_b32 s2, 0x19bb8000
	flat_store_short v[98:99], v0 offset:1536
	v_add_co_u32_e32 v98, vcc, s2, v136
	v_cvt_pk_bf16_f32 v0, v110, s0
	s_nop 0
	v_addc_co_u32_e32 v99, vcc, 0, v137, vcc
	flat_store_short v[98:99], v0
	v_cvt_pk_bf16_f32 v0, v111, s0
	flat_store_short v[98:99], v0 offset:512
	v_cvt_pk_bf16_f32 v0, v112, s0
	flat_store_short v[98:99], v0 offset:1024
	v_cvt_pk_bf16_f32 v0, v113, s0
	s_mov_b32 s8, 0x19bb9000
	flat_store_short v[98:99], v0 offset:1536
	v_add_co_u32_e32 v98, vcc, s8, v136
	v_cvt_pk_bf16_f32 v0, v82, s0
	s_nop 0
	v_addc_co_u32_e32 v99, vcc, 0, v137, vcc
	flat_store_short v[98:99], v0
	v_cvt_pk_bf16_f32 v0, v83, s0
	flat_store_short v[98:99], v0 offset:512
	v_cvt_pk_bf16_f32 v0, v84, s0
	s_mov_b32 s2, 0x19bba000
	flat_store_short v[98:99], v0 offset:1024
	v_cvt_pk_bf16_f32 v0, v85, s0
	v_add_co_u32_e32 v82, vcc, s2, v136
	flat_store_short v[98:99], v0 offset:1536
	v_cvt_pk_bf16_f32 v0, v86, s0
	v_addc_co_u32_e32 v83, vcc, 0, v137, vcc
	flat_store_short v[82:83], v0
	v_cvt_pk_bf16_f32 v0, v87, s0
	flat_store_short v[82:83], v0 offset:512
	v_cvt_pk_bf16_f32 v0, v88, s0
	flat_store_short v[82:83], v0 offset:1024
	v_cvt_pk_bf16_f32 v0, v89, s0
	s_mov_b32 s2, 0x19bbb000
	flat_store_short v[82:83], v0 offset:1536
	v_add_co_u32_e32 v82, vcc, s2, v136
	v_cvt_pk_bf16_f32 v0, v90, s0
	s_nop 0
	v_addc_co_u32_e32 v83, vcc, 0, v137, vcc
	flat_store_short v[82:83], v0
	v_cvt_pk_bf16_f32 v0, v91, s0
	flat_store_short v[82:83], v0 offset:512
	v_cvt_pk_bf16_f32 v0, v92, s0
	flat_store_short v[82:83], v0 offset:1024
	v_cvt_pk_bf16_f32 v0, v93, s0
	s_mov_b32 s2, 0x19bbc000
	flat_store_short v[82:83], v0 offset:1536
	v_add_co_u32_e32 v82, vcc, s2, v136
	v_cvt_pk_bf16_f32 v0, v94, s0
	s_nop 0
	v_addc_co_u32_e32 v83, vcc, 0, v137, vcc
	flat_store_short v[82:83], v0
	v_cvt_pk_bf16_f32 v0, v95, s0
	flat_store_short v[82:83], v0 offset:512
	v_cvt_pk_bf16_f32 v0, v96, s0
	flat_store_short v[82:83], v0 offset:1024
	v_cvt_pk_bf16_f32 v0, v97, s0
	s_mov_b32 s2, 0x19bbd000
	flat_store_short v[82:83], v0 offset:1536
	v_add_co_u32_e32 v82, vcc, s2, v136
	v_cvt_pk_bf16_f32 v0, v66, s0
	s_nop 0
	v_addc_co_u32_e32 v83, vcc, 0, v137, vcc
	flat_store_short v[82:83], v0
	v_cvt_pk_bf16_f32 v0, v67, s0
	flat_store_short v[82:83], v0 offset:512
	v_cvt_pk_bf16_f32 v0, v68, s0
	s_mov_b32 s2, 0x19bbe000
	flat_store_short v[82:83], v0 offset:1024
	v_cvt_pk_bf16_f32 v0, v69, s0
	v_add_co_u32_e32 v66, vcc, s2, v136
	flat_store_short v[82:83], v0 offset:1536
	v_cvt_pk_bf16_f32 v0, v70, s0
	v_addc_co_u32_e32 v67, vcc, 0, v137, vcc
	flat_store_short v[66:67], v0
	v_cvt_pk_bf16_f32 v0, v71, s0
	flat_store_short v[66:67], v0 offset:512
	v_cvt_pk_bf16_f32 v0, v72, s0
	flat_store_short v[66:67], v0 offset:1024
	v_cvt_pk_bf16_f32 v0, v73, s0
	s_mov_b32 s2, 0x19bbf000
	flat_store_short v[66:67], v0 offset:1536
	v_add_co_u32_e32 v66, vcc, s2, v136
	v_cvt_pk_bf16_f32 v0, v74, s0
	s_nop 0
	v_addc_co_u32_e32 v67, vcc, 0, v137, vcc
	flat_store_short v[66:67], v0
	v_cvt_pk_bf16_f32 v0, v75, s0
	flat_store_short v[66:67], v0 offset:512
	v_cvt_pk_bf16_f32 v0, v76, s0
	flat_store_short v[66:67], v0 offset:1024
	v_cvt_pk_bf16_f32 v0, v77, s0
	flat_store_short v[66:67], v0 offset:1536
	v_add_co_u32_e32 v66, vcc, 0x19bc0000, v136
	v_cvt_pk_bf16_f32 v0, v78, s0
	s_nop 0
	v_addc_co_u32_e32 v67, vcc, 0, v137, vcc
	flat_store_short v[66:67], v0
	v_cvt_pk_bf16_f32 v0, v79, s0
	flat_store_short v[66:67], v0 offset:512
	v_cvt_pk_bf16_f32 v0, v80, s0
	flat_store_short v[66:67], v0 offset:1024
	v_cvt_pk_bf16_f32 v0, v81, s0
	flat_store_short v[66:67], v0 offset:1536

; DI f32x16 mfma(bf16x8 a, bf16x8 b, f32x16 c) { return __builtin_amdgcn_mfma_f32_32x32x16_bf16(a, b, c, 0, 0, 0); }
;     ...
;   __syncthreads();
;   DMA_ISSUE(0, 0)
;   asm volatile("s_waitcnt vmcnt(0)" ::: "memory");
;   __builtin_amdgcn_s_barrier();
;   for (int kt = 0; kt < nk; ++kt) {
;     const char* cur = lds + (kt & 1) * DBUF;
;     if (kt + 1 < nk) DMA_ISSUE((kt + 1) & 1, kt + 1)
; #pragma unroll(NTB == 1 ? 2 : 4)
;     for (int s = 0; s < 4; ++s) {
;       const int ro = ((2 * s + hh) ^ xr) * 16;
;       bf16x8 bfr[NTB];
; #pragma unroll
;       for (int tb = 0; tb < NTB; ++tb) bfr[tb] = *(const bf16x8*)(cur + bbase + tb * 32 * DROW + ro);
; #pragma unroll
;       for (int fb = 0; fb < NFB; ++fb) {
;         const bf16x8 afr = *(const bf16x8*)(cur + abase + fb * 32 * DROW + ro);
; #pragma unroll
;         for (int tb = 0; tb < NTB; ++tb) acc[tb * NFB + fb] = mfma(afr, bfr[tb], acc[tb * NFB + fb]);
;       }
;     }
;     asm volatile("s_waitcnt vmcnt(0) lgkmcnt(0)" ::: "memory");
;     __builtin_amdgcn_s_barrier();
;   }
.LBB0_206:
	s_add_i32 s5, s1, 0xffff0000
	s_and_b32 s5, s5, 0x10000
	v_add_u32_e32 v184, s5, v137
	v_add_u32_e32 v186, s5, v139
	v_add_u32_e32 v189, v184, v138
	v_add_u32_e32 v194, v186, v138
	ds_read_b128 v[234:237], v189 offset:32768
	ds_read_b128 v[238:241], v189 offset:36864
	ds_read_b128 v[250:253], v194
	ds_read_b128 v[180:183], v194 offset:4096
	ds_read_b128 v[190:193], v194 offset:8192
	ds_read_b128 v[152:155], v194 offset:12288
	v_add_u32_e32 v189, v184, v136
	v_add_u32_e32 v194, v186, v136
	ds_read_b128 v[242:245], v189 offset:32768
	ds_read_b128 v[246:249], v189 offset:36864
	s_waitcnt lgkmcnt(5)
	v_mfma_f32_32x32x16_bf16 v[114:129], v[250:253], v[234:237], v[114:129]
	v_mfma_f32_32x32x16_bf16 v[50:65], v[250:253], v[238:241], v[50:65]
	ds_read_b128 v[250:253], v194
	s_and_b32 s9, s1, 0x10000
	v_add_u32_e32 v148, s9, v135
	v_lshl_add_u64 v[140:141], v[130:131], 0, s[6:7]
	v_readfirstlane_b32 s9, v148
	v_add_u32_e32 v149, 0x2000, v148
	v_lshl_add_u64 v[142:143], v[140:141], 0, s[84:85]
	s_mov_b32 m0, s9
	v_readfirstlane_b32 s9, v149
	v_add_u32_e32 v149, 0x4000, v148
	global_load_lds_dwordx4 v[142:143], off
	v_lshl_add_u64 v[142:143], v[140:141], 0, s[90:91]
	s_mov_b32 m0, s9
	v_readfirstlane_b32 s9, v149
	global_load_lds_dwordx4 v[142:143], off
	s_waitcnt lgkmcnt(5)
	v_mfma_f32_32x32x16_bf16 v[98:113], v[180:183], v[234:237], v[98:113]
	v_mfma_f32_32x32x16_bf16 v[34:49], v[180:183], v[238:241], v[34:49]
	ds_read_b128 v[180:183], v194 offset:4096
	v_lshl_add_u64 v[142:143], v[140:141], 0, s[48:49]
	s_mov_b32 m0, s9
	v_lshl_add_u64 v[140:141], v[140:141], 0, s[50:51]
	global_load_lds_dwordx4 v[142:143], off
	v_add_u32_e32 v142, 0x6000, v148
	v_add_u32_e32 v149, 0x8000, v148
	v_readfirstlane_b32 s9, v142
	s_mov_b32 m0, s9
	v_readfirstlane_b32 s9, v149
	global_load_lds_dwordx4 v[140:141], off
	s_waitcnt lgkmcnt(5)
	v_mfma_f32_32x32x16_bf16 v[82:97], v[190:193], v[234:237], v[82:97]
	v_mfma_f32_32x32x16_bf16 v[18:33], v[190:193], v[238:241], v[18:33]
	ds_read_b128 v[190:193], v194 offset:8192
	v_lshl_add_u64 v[140:141], v[132:133], 0, s[6:7]
	v_add_u32_e32 v149, 0xa000, v148
	v_lshl_add_u64 v[142:143], v[140:141], 0, s[10:11]
	s_mov_b32 m0, s9
	v_readfirstlane_b32 s9, v149
	v_add_u32_e32 v149, 0xc000, v148
	global_load_lds_dwordx4 v[142:143], off
	v_lshl_add_u64 v[142:143], v[140:141], 0, s[12:13]
	s_mov_b32 m0, s9
	v_readfirstlane_b32 s9, v149
	s_add_i32 s5, s1, 0xffff0000
	global_load_lds_dwordx4 v[142:143], off
	s_waitcnt lgkmcnt(5)
	v_mfma_f32_32x32x16_bf16 v[66:81], v[152:155], v[234:237], v[66:81]
	v_mfma_f32_32x32x16_bf16 v[2:17], v[152:155], v[238:241], v[2:17]
	ds_read_b128 v[152:155], v194 offset:12288
	v_lshl_add_u64 v[142:143], v[140:141], 0, s[14:15]
	s_mov_b32 m0, s9
	s_and_b32 s5, s5, 0x10000
	global_load_lds_dwordx4 v[142:143], off
	v_add_u32_e32 v142, 0xe000, v148
	s_add_i32 s5, s5, 0
	v_readfirstlane_b32 s9, v142
	v_lshl_add_u64 v[140:141], v[140:141], 0, s[40:41]
	s_mov_b32 m0, s9
	v_add_u32_e32 v156, s5, v137
	v_add_u32_e32 v157, s5, v139
	global_load_lds_dwordx4 v[140:141], off
	v_add_u32_e32 v189, v184, v134
	v_add_u32_e32 v194, v186, v134
	ds_read_b128 v[234:237], v189 offset:32768
	ds_read_b128 v[238:241], v189 offset:36864
	s_waitcnt lgkmcnt(5)
	v_mfma_f32_32x32x16_bf16 v[114:129], v[250:253], v[242:245], v[114:129]
	v_mfma_f32_32x32x16_bf16 v[50:65], v[250:253], v[246:249], v[50:65]
	ds_read_b128 v[250:253], v194
	s_add_u32 s6, s6, 0x80
	s_addc_u32 s7, s7, 0
	s_add_i32 s1, s1, 0x10000
	s_cmpk_eq_i32 s6, 0x780
	s_waitcnt lgkmcnt(5)
	v_mfma_f32_32x32x16_bf16 v[98:113], v[180:183], v[242:245], v[98:113]
	v_mfma_f32_32x32x16_bf16 v[34:49], v[180:183], v[246:249], v[34:49]
	ds_read_b128 v[180:183], v194 offset:4096
	s_waitcnt lgkmcnt(5)
	v_mfma_f32_32x32x16_bf16 v[82:97], v[190:193], v[242:245], v[82:97]
	v_mfma_f32_32x32x16_bf16 v[18:33], v[190:193], v[246:249], v[18:33]
	ds_read_b128 v[190:193], v194 offset:8192
	s_waitcnt lgkmcnt(5)
	v_mfma_f32_32x32x16_bf16 v[66:81], v[152:155], v[242:245], v[66:81]
	v_mfma_f32_32x32x16_bf16 v[2:17], v[152:155], v[246:249], v[2:17]
	ds_read_b128 v[152:155], v194 offset:12288
	v_add_u32_e32 v189, v184, v0
	v_add_u32_e32 v194, v186, v0
	ds_read_b128 v[242:245], v189 offset:32768
	ds_read_b128 v[246:249], v189 offset:36864
	s_waitcnt lgkmcnt(5)
	v_mfma_f32_32x32x16_bf16 v[114:129], v[250:253], v[234:237], v[114:129]
	v_mfma_f32_32x32x16_bf16 v[50:65], v[250:253], v[238:241], v[50:65]
	ds_read_b128 v[250:253], v194
	s_waitcnt lgkmcnt(5)
	v_mfma_f32_32x32x16_bf16 v[98:113], v[180:183], v[234:237], v[98:113]
	v_mfma_f32_32x32x16_bf16 v[34:49], v[180:183], v[238:241], v[34:49]
	ds_read_b128 v[180:183], v194 offset:4096
	s_waitcnt lgkmcnt(5)
	v_mfma_f32_32x32x16_bf16 v[82:97], v[190:193], v[234:237], v[82:97]
	v_mfma_f32_32x32x16_bf16 v[18:33], v[190:193], v[238:241], v[18:33]
	ds_read_b128 v[190:193], v194 offset:8192
	s_waitcnt lgkmcnt(5)
	v_mfma_f32_32x32x16_bf16 v[66:81], v[152:155], v[234:237], v[66:81]
	v_mfma_f32_32x32x16_bf16 v[2:17], v[152:155], v[238:241], v[2:17]
	ds_read_b128 v[152:155], v194 offset:12288
	s_waitcnt lgkmcnt(3)
	v_mfma_f32_32x32x16_bf16 v[114:129], v[250:253], v[242:245], v[114:129]
	v_mfma_f32_32x32x16_bf16 v[50:65], v[250:253], v[246:249], v[50:65]
	s_waitcnt lgkmcnt(2)
	v_mfma_f32_32x32x16_bf16 v[98:113], v[180:183], v[242:245], v[98:113]
	v_mfma_f32_32x32x16_bf16 v[34:49], v[180:183], v[246:249], v[34:49]
	s_waitcnt lgkmcnt(1)
	v_mfma_f32_32x32x16_bf16 v[82:97], v[190:193], v[242:245], v[82:97]
	v_mfma_f32_32x32x16_bf16 v[18:33], v[190:193], v[246:249], v[18:33]
	s_waitcnt vmcnt(0) lgkmcnt(0)
	s_barrier
; DI f32x16 mfma(bf16x8 a, bf16x8 b, f32x16 c) { return __builtin_amdgcn_mfma_f32_32x32x16_bf16(a, b, c, 0, 0, 0); }
;     ...
;   for (int kt = 0; kt < nk; ++kt) {
;     const char* cur = lds + (kt & 1) * DBUF;
;     if (kt + 1 < nk) DMA_ISSUE((kt + 1) & 1, kt + 1)
; #pragma unroll(NTB == 1 ? 2 : 4)
;     for (int s = 0; s < 4; ++s) {
;       const int ro = ((2 * s + hh) ^ xr) * 16;
;       bf16x8 bfr[NTB];
; #pragma unroll
;       for (int tb = 0; tb < NTB; ++tb) bfr[tb] = *(const bf16x8*)(cur + bbase + tb * 32 * DROW + ro);
; #pragma unroll
;       for (int fb = 0; fb < NFB; ++fb) {
;         const bf16x8 afr = *(const bf16x8*)(cur + abase + fb * 32 * DROW + ro);
; #pragma unroll
;         for (int tb = 0; tb < NTB; ++tb) acc[tb * NFB + fb] = mfma(afr, bfr[tb], acc[tb * NFB + fb]);
;       }
;     }
;     asm volatile("s_waitcnt vmcnt(0) lgkmcnt(0)" ::: "memory");
;     __builtin_amdgcn_s_barrier();
;   }
	v_mfma_f32_32x32x16_bf16 v[66:81], v[152:155], v[242:245], v[66:81]
	v_mfma_f32_32x32x16_bf16 v[2:17], v[152:155], v[246:249], v[2:17]
	s_cbranch_scc0 .LBB0_206
	s_add_i32 s1, 0, 0x10000
	v_add_u32_e32 v160, s1, v139
	v_add_u32_e32 v135, v160, v138
	ds_read_b128 v[130:133], v135
	v_add_u32_e32 v161, s1, v137
	v_add_u32_e32 v137, v161, v138
	ds_read_b128 v[138:141], v137 offset:32768
	ds_read_b128 v[148:151], v137 offset:36864
	ds_read_b128 v[152:155], v135 offset:4096
	s_mov_b32 s1, 0x20000
	s_waitcnt lgkmcnt(0)
	v_mfma_f32_32x32x16_bf16 v[98:113], v[152:155], v[138:141], v[98:113]
	s_mov_b64 s[64:65], s[30:31]
	v_mfma_f32_32x32x16_bf16 v[114:129], v[130:133], v[138:141], v[114:129]
	v_mfma_f32_32x32x16_bf16 v[50:65], v[130:133], v[148:151], v[50:65]
	v_mfma_f32_32x32x16_bf16 v[34:49], v[152:155], v[148:151], v[34:49]
	ds_read_b128 v[130:133], v135 offset:8192
	ds_read_b128 v[152:155], v135 offset:12288
	v_add_u32_e32 v135, v160, v136
	s_waitcnt lgkmcnt(0)
	v_mfma_f32_32x32x16_bf16 v[82:97], v[130:133], v[138:141], v[82:97]
	v_mfma_f32_32x32x16_bf16 v[18:33], v[130:133], v[148:151], v[18:33]
	ds_read_b128 v[130:133], v135
	v_mfma_f32_32x32x16_bf16 v[66:81], v[152:155], v[138:141], v[66:81]
	v_add_u32_e32 v140, v161, v136
	v_mfma_f32_32x32x16_bf16 v[2:17], v[152:155], v[148:151], v[2:17]
	ds_read_b128 v[136:139], v140 offset:32768
	ds_read_b128 v[140:143], v140 offset:36864
	ds_read_b128 v[148:151], v135 offset:4096
	s_waitcnt lgkmcnt(0)
	v_mfma_f32_32x32x16_bf16 v[114:129], v[130:133], v[136:139], v[114:129]
	v_mfma_f32_32x32x16_bf16 v[50:65], v[130:133], v[140:143], v[50:65]
	v_mfma_f32_32x32x16_bf16 v[98:113], v[148:151], v[136:139], v[98:113]
	v_mfma_f32_32x32x16_bf16 v[34:49], v[148:151], v[140:143], v[34:49]
	ds_read_b128 v[130:133], v135 offset:8192
	ds_read_b128 v[148:151], v135 offset:12288
	s_waitcnt lgkmcnt(0)
	v_mfma_f32_32x32x16_bf16 v[82:97], v[130:133], v[136:139], v[82:97]
	v_mfma_f32_32x32x16_bf16 v[66:81], v[148:151], v[136:139], v[66:81]
	v_add_u32_e32 v138, v160, v134
	v_add_u32_e32 v139, v161, v134
	v_mfma_f32_32x32x16_bf16 v[18:33], v[130:133], v[140:143], v[18:33]
	ds_read_b128 v[130:133], v138
	ds_read_b128 v[134:137], v139 offset:32768
	ds_read_b128 v[152:155], v139 offset:36864
	ds_read_b128 v[156:159], v138 offset:4096
	ds_read_b128 v[162:165], v138 offset:8192
	ds_read_b128 v[172:175], v138 offset:12288
	v_add_u32_e32 v138, v161, v0
	v_add_u32_e32 v0, v160, v0
	v_mfma_f32_32x32x16_bf16 v[2:17], v[148:151], v[140:143], v[2:17]
	v_lshl_or_b32 v148, s4, 8, v170
	v_ashrrev_i32_e32 v149, 31, v148
	v_lshl_add_u64 v[160:161], v[148:149], 2, s[24:25]
	ds_read_b128 v[176:179], v138 offset:32768
	ds_read_b128 v[138:141], v138 offset:36864
	ds_read_b128 v[180:183], v0
	ds_read_b128 v[232:235], v0 offset:4096
	ds_read_b128 v[236:239], v0 offset:8192
	ds_read_b128 v[240:243], v0 offset:12288
	s_waitcnt vmcnt(0) lgkmcnt(0)
	s_waitcnt lgkmcnt(0)
	v_mfma_f32_32x32x16_bf16 v[114:129], v[130:133], v[134:137], v[114:129]
	s_barrier
; DI void g1_epilogue(const Params& p, int l, int t, int ft, f32x16* acc, bool do_atomic) {
;   char* ws = get_ws(p);
;   const int tid_ = get_tid(); const int lane = tid_ & 63, wave = tid_ >> 6, l32 = lane & 31, hh = lane >> 5;
;   const int b = t >> 12, s = t & 4095;
;   if (ft < 5) {
;     u16* dst; float* ssp;
;     if (ft < 3) { dst = (u16*)(ws + R_CQ) + (size_t)t * 384 + ft * 128; ssp = (float*)(ws + OFF_SSQ) + (size_t)ft * T_TOK + t; }
;     else { dst = (u16*)(ws + R_CKV) + (size_t)t * 256 + (ft - 3) * 128; ssp = (float*)(ws + OFF_SSKV) + (size_t)(ft - 3) * T_TOK + t; }
;     float ss = 0.f;
; #pragma unroll
;     for (int fb = 0; fb < 4; ++fb) {
;       ss += sumsq16(acc[fb]);
;       st_blk_plain(dst + fb * 32, hh, acc[fb]);
;     }
;     ss = xsum32(ss);
;     if (hh == 0) *ssp = ss;
;   } else if (ft < 13) {
;     const bool isq = ft < 9; const int head = isq ? ft - 5 : ft - 9;
;     const float* g = (isq ? p.g_diff_q : p.g_diff_k) + l * 64;
;     u16* base = (u16*)(ws + (isq ? R_DQ : R_DK));
;     const float mul = isq ? 0.125f * LOG2E : 1.f;
; #pragma unroll
;     for (int c = 0; c < 2; ++c) {
;       float ss = sumsq16(acc[2 * c]) + sumsq16(acc[2 * c + 1]);
;       ss = xsum32(ss);
;       const float rstd = rsqrtf(ss * (1.f / 64.f) + EPS) * mul;
;       u16* dst = base + (((size_t)(b * 4 + head) * 2 + c) * 4096 + s) * 64;
; #pragma unroll
;       for (int fbb = 0; fbb < 2; ++fbb) st_blk_scaled(dst + fbb * 32, hh, acc[2 * c + fbb], rstd, g + fbb * 32);
;     }
;   } else if (ft < 17) {
;     const int head = ft - 13;
;     u16* dst = (u16*)(ws + R_DV) + ((size_t)(b * 4 + head) * 128) * 4096 + perm16(s);
; #pragma unroll
;     for (int fb = 0; fb < 4; ++fb)
; #pragma unroll
;       for (int i = 0; i < 16; ++i) {
;         const int d = fb * 32 + 8 * (i >> 2) + 4 * hh + (i & 3);
;         dst[(size_t)d * 4096] = tobf(acc[fb][i]);
;       }
;   } else if (ft < 21) {
;     const int head = ft - 17;
; __global__ void __launch_bounds__(512) mega(Params p) {
;     ...
;             const float r1 = rstd4((const float*)(ws + OFF_SSX1) + (size_t)(l & 1) * 4 * T_TOK, t);
; #pragma unroll
;             for (int fb = 0; fb < 4; ++fb)
; #pragma unroll
;               for (int i = 0; i < 16; ++i) acc[tb * 4 + fb][i] *= r1;
;             g1_epilogue(p, l, t, ft * 2 + wf, acc + tb * 4, (p.flags & 1) == 0);
	v_mfma_f32_32x32x16_bf16 v[50:65], v[130:133], v[152:155], v[50:65]
	v_add_co_u32_e32 v130, vcc, s1, v160
	s_mov_b32 s1, 0x40000
	s_nop 0
	v_addc_co_u32_e32 v131, vcc, 0, v161, vcc
	v_add_co_u32_e32 v132, vcc, s1, v160
	s_mov_b32 s1, 0x60000
	s_nop 0
	v_addc_co_u32_e32 v133, vcc, 0, v161, vcc
	v_add_co_u32_e32 v142, vcc, s1, v160
	v_mfma_f32_32x32x16_bf16 v[98:113], v[156:159], v[134:137], v[98:113]
	s_nop 0
	v_addc_co_u32_e32 v143, vcc, 0, v161, vcc
	v_mfma_f32_32x32x16_bf16 v[34:49], v[156:159], v[152:155], v[34:49]
	flat_load_dword v0, v[160:161]
	flat_load_dword v157, v[130:131]
	s_nop 0
	flat_load_dword v132, v[132:133]
	s_nop 0
	flat_load_dword v133, v[142:143]
	v_lshl_add_u32 v156, s0, 1, v146
	s_ashr_i32 s0, s8, 2
	v_subrev_co_u32_e32 v130, vcc, 17, v156
	s_and_b32 s0, s0, -4
	v_add_u32_e32 v130, s0, v130
	v_mfma_f32_32x32x16_bf16 v[82:97], v[162:165], v[134:137], v[82:97]
	s_xor_b64 s[42:43], vcc, -1
	v_subrev_co_u32_e32 v150, vcc, 13, v156
	v_ashrrev_i32_e32 v131, 31, v130
	v_lshlrev_b64 v[142:143], 20, v[130:131]
	v_add_u32_e32 v130, s0, v150
	v_ashrrev_i32_e32 v131, 31, v130
	v_mfma_f32_32x32x16_bf16 v[66:81], v[172:175], v[134:137], v[66:81]
	s_xor_b64 s[52:53], vcc, -1
	v_lshlrev_b64 v[150:151], 20, v[130:131]
	v_cmp_gt_u32_e32 vcc, 9, v156
	v_mov_b32_e32 v130, 0x3e38aa3b
	v_readlane_b32 s8, v255, 14
	v_cndmask_b32_e32 v171, 1.0, v130, vcc
	v_mov_b32_e32 v130, 0xb9b1000
	v_mfma_f32_32x32x16_bf16 v[18:33], v[162:165], v[152:155], v[18:33]
	v_mov_b32_e32 v131, 0x99b1000
	v_readlane_b32 s19, v255, 25
	v_readlane_b32 s21, v255, 27
	v_cndmask_b32_e32 v158, v130, v131, vcc
	v_readlane_b32 s18, v255, 24
	v_readlane_b32 s20, v255, 26
	v_mov_b32_e32 v130, s21
	v_mfma_f32_32x32x16_bf16 v[2:17], v[172:175], v[152:155], v[2:17]
	v_mov_b32_e32 v131, s19
	v_cndmask_b32_e32 v131, v130, v131, vcc
	v_mov_b32_e32 v130, s20
	v_mov_b32_e32 v135, s18
	v_cndmask_b32_e32 v130, v130, v135, vcc
	v_cndmask_b32_e64 v134, -9, -5, vcc
	v_lshl_add_u64 v[154:155], s[74:75], 2, v[130:131]
	v_mfma_f32_32x32x16_bf16 v[114:129], v[180:183], v[176:179], v[114:129]
	v_add3_u32 v130, v156, s0, v134
	v_cmp_lt_i32_e64 s[6:7], 4, v156
	v_cmp_lt_u32_e64 s[4:5], 20, v156
	v_mov_b32_e32 v159, v1
	v_cmp_lt_i32_e64 s[0:1], 2, v156
	v_readlane_b32 s9, v255, 15
	v_mfma_f32_32x32x16_bf16 v[98:113], v[232:235], v[176:179], v[98:113]
	v_readlane_b32 s10, v255, 16
	v_readlane_b32 s11, v255, 17
	v_readlane_b32 s12, v255, 18
	v_readlane_b32 s13, v255, 19
	v_readlane_b32 s14, v255, 20
	v_readlane_b32 s15, v255, 21
	v_readlane_b32 s16, v255, 22
	v_mfma_f32_32x32x16_bf16 v[82:97], v[236:239], v[176:179], v[82:97]
	v_readlane_b32 s17, v255, 23
	v_readlane_b32 s22, v255, 28
	v_readlane_b32 s23, v255, 29
	s_waitcnt vmcnt(0) lgkmcnt(0)
	v_add_f32_e32 v0, v0, v157
	v_add_f32_e32 v0, v0, v132
	v_add_f32_e32 v0, v0, v133
	v_fmamk_f32 v0, v0, 0x3a800000, v144
	v_mul_f32_e32 v131, 0x4b800000, v0
	v_cmp_gt_f32_e32 vcc, s47, v0
	v_mfma_f32_32x32x16_bf16 v[66:81], v[240:243], v[176:179], v[66:81]
	s_nop 0
	v_cndmask_b32_e32 v0, v0, v131, vcc
	v_rsq_f32_e32 v0, v0
	v_ashrrev_i32_e32 v131, 31, v130
	v_lshlrev_b64 v[152:153], 20, v[130:131]
	v_mul_f32_e32 v130, 0x45800000, v0
	v_mfma_f32_32x32x16_bf16 v[50:65], v[180:183], v[138:141], v[50:65]
	v_cndmask_b32_e32 v0, v0, v130, vcc
	v_mul_f32_e64 v134, v0, v114
	v_mul_f32_e64 v135, v0, v115
	v_mul_f32_e64 v136, v0, v116
	v_mul_f32_e64 v137, v0, v117
	v_pk_mul_f32 v[130:131], v[0:1], v[118:119] op_sel_hi:[0,1]
	v_pk_mul_f32 v[132:133], v[0:1], v[120:121] op_sel_hi:[0,1]
	v_pk_mul_f32 v[118:119], v[0:1], v[122:123] op_sel_hi:[0,1]
	v_pk_mul_f32 v[120:121], v[0:1], v[124:125] op_sel_hi:[0,1]
	v_mfma_f32_32x32x16_bf16 v[34:49], v[232:235], v[138:141], v[34:49]
	v_mul_f32_e64 v114, v0, v126
	v_mul_f32_e64 v115, v0, v127
	v_mul_f32_e64 v116, v0, v128
	v_mul_f32_e64 v117, v0, v129
	v_mul_f32_e64 v166, v0, v98
	v_mul_f32_e64 v167, v0, v99
	v_pk_mul_f32 v[164:165], v[0:1], v[100:101] op_sel_hi:[0,1]
	v_pk_mul_f32 v[162:163], v[0:1], v[102:103] op_sel_hi:[0,1]
	v_pk_mul_f32 v[128:129], v[0:1], v[104:105] op_sel_hi:[0,1]
	v_pk_mul_f32 v[126:127], v[0:1], v[106:107] op_sel_hi:[0,1]
	v_mfma_f32_32x32x16_bf16 v[18:33], v[236:239], v[138:141], v[18:33]
	v_mul_f32_e64 v124, v0, v108
	v_mul_f32_e64 v125, v0, v109
	v_mul_f32_e64 v122, v0, v110
	v_mul_f32_e64 v123, v0, v111
	v_mul_f32_e64 v110, v0, v112
	v_mul_f32_e64 v111, v0, v113
	v_pk_mul_f32 v[108:109], v[0:1], v[82:83] op_sel_hi:[0,1]
	v_pk_mul_f32 v[106:107], v[0:1], v[84:85] op_sel_hi:[0,1]
	v_pk_mul_f32 v[104:105], v[0:1], v[86:87] op_sel_hi:[0,1]
	v_pk_mul_f32 v[102:103], v[0:1], v[88:89] op_sel_hi:[0,1]
	v_mfma_f32_32x32x16_bf16 v[2:17], v[240:243], v[138:141], v[2:17]
	v_mul_f32_e64 v100, v0, v90
	v_mul_f32_e64 v101, v0, v91
	v_mul_f32_e64 v98, v0, v92
	v_mul_f32_e64 v99, v0, v93
	v_mul_f32_e64 v94, v0, v94
	v_mul_f32_e64 v95, v0, v95
	v_pk_mul_f32 v[92:93], v[0:1], v[96:97] op_sel_hi:[0,1]
	v_pk_mul_f32 v[90:91], v[0:1], v[66:67] op_sel_hi:[0,1]
	v_pk_mul_f32 v[88:89], v[0:1], v[68:69] op_sel_hi:[0,1]
	v_pk_mul_f32 v[86:87], v[0:1], v[70:71] op_sel_hi:[0,1]
	v_pk_mul_f32 v[84:85], v[0:1], v[72:73] op_sel_hi:[0,1]
	v_pk_mul_f32 v[82:83], v[0:1], v[74:75] op_sel_hi:[0,1]
	v_pk_mul_f32 v[74:75], v[0:1], v[76:77] op_sel_hi:[0,1]
	v_pk_mul_f32 v[72:73], v[0:1], v[78:79] op_sel_hi:[0,1]
	v_pk_mul_f32 v[70:71], v[0:1], v[80:81] op_sel_hi:[0,1]
	v_mov_b32_e32 v0, v145
	s_nop 0
	v_bfe_u32 v78, v0, 5, 1
	s_and_saveexec_b64 s[8:9], s[6:7]
	s_xor_b64 s[66:67], exec, s[8:9]
	s_cbranch_execz .LBB0_221
	v_and_b32_e32 v68, 0xfdf, v148
	s_and_saveexec_b64 s[8:9], s[52:53]
	s_xor_b64 s[10:11], exec, s[8:9]
	s_cbranch_execz .LBB0_218
	s_and_saveexec_b64 s[8:9], s[42:43]
	s_xor_b64 s[34:35], exec, s[8:9]
	s_cbranch_execz .LBB0_215
	s_and_saveexec_b64 s[8:9], s[4:5]
	s_xor_b64 s[8:9], exec, s[8:9]
	s_cbranch_execz .LBB0_212
	v_lshlrev_b64 v[66:67], 7, v[148:149]
	v_lshl_add_u64 v[66:67], s[64:65], 0, v[66:67]
	v_lshlrev_b32_e32 v0, 4, v78
	v_lshl_add_u64 v[66:67], v[66:67], 0, v[0:1]
	s_mov_b64 s[68:69], 0x95b1000
	v_lshl_add_u64 v[68:69], v[66:67], 0, s[68:69]
	v_add_co_u32_e32 v66, vcc, 0x95b1000, v66
	s_nop 1
	v_addc_co_u32_e32 v67, vcc, 0, v67, vcc
	flat_store_dwordx4 v[66:67], v[134:137]
	flat_store_dwordx4 v[68:69], v[130:133] offset:32
	flat_store_dwordx4 v[68:69], v[118:121] offset:64
	flat_store_dwordx4 v[68:69], v[114:117] offset:96
